# step8 with deeper residual-load prefetch (2-3 iterations ahead where free registers allow) in the first-residual and LN-residual GEMM epilogues
# baseline (speedup 1.0000x reference)
.LBB0_678:
	v_lshl_add_u32 v146, s77, 8, v188
	v_lshl_or_b32 v156, s78, 8, v192
	v_ashrrev_i32_e32 v147, 31, v146
	v_ashrrev_i32_e32 v157, 31, v156
	v_lshlrev_b64 v[162:163], 11, v[146:147]
	v_lshl_add_u64 v[148:149], v[162:163], 0, v[156:157]
	v_lshl_add_u64 v[168:169], v[148:149], 2, s[48:49]
	global_load_dwordx4 v[234:237], v[168:169], off
	global_load_dwordx4 v[238:241], v[168:169], off offset:16
	v_or_b32_e32 v144, 16, v146
	v_ashrrev_i32_e32 v145, 31, v144
	v_lshl_add_u64 v[154:155], v[148:149], 1, s[16:17]
	v_lshlrev_b64 v[160:161], 11, v[144:145]
	v_lshl_add_u64 v[158:159], v[160:161], 0, v[156:157]
	v_lshl_add_u64 v[164:165], v[158:159], 2, s[48:49]
	v_lshl_add_u64 v[158:159], v[158:159], 1, s[16:17]
	global_load_dwordx4 v[242:245], v[164:165], off
	global_load_dwordx4 v[246:249], v[164:165], off offset:16
	s_waitcnt vmcnt(2)
	v_pk_fma_f32 v[148:149], v[236:237], s[28:29], v[122:123] op_sel_hi:[1,0,1]
	v_pk_fma_f32 v[150:151], v[234:235], s[28:29], v[120:121] op_sel_hi:[1,0,1]
	v_pk_fma_f32 v[126:127], v[240:241], s[28:29], v[126:127] op_sel_hi:[1,0,1]
	v_pk_fma_f32 v[152:153], v[238:239], s[28:29], v[124:125] op_sel_hi:[1,0,1]
	v_cvt_pk_bf16_f32 v120, v150, v151
	v_cvt_pk_bf16_f32 v121, v148, v149
	v_cvt_pk_bf16_f32 v122, v152, v153
	v_cvt_pk_bf16_f32 v123, v126, v127
	global_store_dwordx4 v[154:155], v[120:123], off
	s_nop 0
	s_nop 0
	v_or_b32_e32 v120, 32, v146
	v_ashrrev_i32_e32 v121, 31, v120
	v_lshlrev_b64 v[166:167], 11, v[120:121]
	v_lshl_add_u64 v[154:155], v[166:167], 0, v[156:157]
	v_lshl_add_u64 v[170:171], v[154:155], 2, s[48:49]
	global_load_dwordx4 v[208:211], v[170:171], off
	global_load_dwordx4 v[212:215], v[170:171], off offset:16
	v_lshl_add_u64 v[154:155], v[154:155], 1, s[16:17]
	s_waitcnt vmcnt(3)
	v_pk_fma_f32 v[122:123], v[244:245], s[28:29], v[118:119] op_sel_hi:[1,0,1]
	v_pk_fma_f32 v[124:125], v[242:243], s[28:29], v[116:117] op_sel_hi:[1,0,1]
	v_pk_fma_f32 v[116:117], v[248:249], s[28:29], v[114:115] op_sel_hi:[1,0,1]
	v_pk_fma_f32 v[118:119], v[246:247], s[28:29], v[112:113] op_sel_hi:[1,0,1]
	v_cvt_pk_bf16_f32 v112, v124, v125
	v_cvt_pk_bf16_f32 v113, v122, v123
	v_cvt_pk_bf16_f32 v114, v118, v119
	v_cvt_pk_bf16_f32 v115, v116, v117
	global_store_dwordx4 v[158:159], v[112:115], off
	s_nop 0
	s_nop 0
	v_or_b32_e32 v112, 48, v146
	v_ashrrev_i32_e32 v113, 31, v112
	v_lshlrev_b64 v[172:173], 11, v[112:113]
	v_lshl_add_u64 v[186:187], v[172:173], 0, v[156:157]
	v_lshl_add_u64 v[174:175], v[186:187], 2, s[48:49]
	global_load_dwordx4 v[234:237], v[174:175], off
	global_load_dwordx4 v[238:241], v[174:175], off offset:16
	v_lshl_add_u64 v[186:187], v[186:187], 1, s[16:17]
	s_waitcnt vmcnt(3)
	v_pk_fma_f32 v[110:111], v[210:211], s[28:29], v[110:111] op_sel_hi:[1,0,1]
	v_pk_fma_f32 v[114:115], v[208:209], s[28:29], v[108:109] op_sel_hi:[1,0,1]
	v_pk_fma_f32 v[106:107], v[214:215], s[28:29], v[106:107] op_sel_hi:[1,0,1]
	v_pk_fma_f32 v[108:109], v[212:213], s[28:29], v[104:105] op_sel_hi:[1,0,1]
	v_cvt_pk_bf16_f32 v176, v114, v115
	v_cvt_pk_bf16_f32 v177, v110, v111
	v_cvt_pk_bf16_f32 v178, v108, v109
	v_cvt_pk_bf16_f32 v179, v106, v107
	global_store_dwordx4 v[154:155], v[176:179], off
	s_nop 0
	s_nop 0
	v_add_u32_e32 v104, 0x80, v146
	v_ashrrev_i32_e32 v105, 31, v104
	v_lshlrev_b64 v[158:159], 11, v[104:105]
	v_lshl_add_u64 v[154:155], v[158:159], 0, v[156:157]
	v_lshl_add_u64 v[176:177], v[154:155], 2, s[48:49]
	global_load_dwordx4 v[242:245], v[176:177], off
	global_load_dwordx4 v[246:249], v[176:177], off offset:16
	v_lshl_add_u64 v[154:155], v[154:155], 1, s[16:17]
	s_waitcnt vmcnt(3)
	v_pk_fma_f32 v[102:103], v[236:237], s[28:29], v[102:103] op_sel_hi:[1,0,1]
	v_pk_fma_f32 v[100:101], v[234:235], s[28:29], v[100:101] op_sel_hi:[1,0,1]
	v_pk_fma_f32 v[98:99], v[240:241], s[28:29], v[98:99] op_sel_hi:[1,0,1]
	v_pk_fma_f32 v[96:97], v[238:239], s[28:29], v[96:97] op_sel_hi:[1,0,1]
	v_cvt_pk_bf16_f32 v178, v100, v101
	v_cvt_pk_bf16_f32 v179, v102, v103
	v_cvt_pk_bf16_f32 v180, v96, v97
	v_cvt_pk_bf16_f32 v181, v98, v99
	global_store_dwordx4 v[186:187], v[178:181], off
	s_nop 0
	s_nop 0
	v_add_u32_e32 v178, 0x90, v146
	v_ashrrev_i32_e32 v179, 31, v178
	v_lshlrev_b64 v[178:179], 11, v[178:179]
	v_lshl_add_u64 v[186:187], v[178:179], 0, v[156:157]
	v_lshl_add_u64 v[180:181], v[186:187], 2, s[48:49]
	global_load_dwordx4 v[208:211], v[180:181], off
	global_load_dwordx4 v[212:215], v[180:181], off offset:16
	s_waitcnt vmcnt(3)
	v_pk_fma_f32 v[94:95], v[244:245], s[28:29], v[94:95] op_sel_hi:[1,0,1]
	v_pk_fma_f32 v[92:93], v[242:243], s[28:29], v[92:93] op_sel_hi:[1,0,1]
	v_pk_fma_f32 v[90:91], v[248:249], s[28:29], v[90:91] op_sel_hi:[1,0,1]
	v_pk_fma_f32 v[88:89], v[246:247], s[28:29], v[88:89] op_sel_hi:[1,0,1]
	v_cvt_pk_bf16_f32 v182, v92, v93
	v_cvt_pk_bf16_f32 v183, v94, v95
	v_cvt_pk_bf16_f32 v184, v88, v89
	v_cvt_pk_bf16_f32 v185, v90, v91
	global_store_dwordx4 v[154:155], v[182:185], off
	s_nop 0
	s_nop 0
	v_add_u32_e32 v154, 0xa0, v146
	v_ashrrev_i32_e32 v155, 31, v154
	v_lshlrev_b64 v[182:183], 11, v[154:155]
	v_lshl_add_u64 v[154:155], v[186:187], 1, s[16:17]
	v_lshl_add_u64 v[204:205], v[182:183], 0, v[156:157]
	v_lshl_add_u64 v[184:185], v[204:205], 2, s[48:49]
	global_load_dwordx4 v[234:237], v[184:185], off
	global_load_dwordx4 v[238:241], v[184:185], off offset:16
	v_lshl_add_u64 v[204:205], v[204:205], 1, s[16:17]
	s_waitcnt vmcnt(3)
	v_pk_fma_f32 v[86:87], v[210:211], s[28:29], v[86:87] op_sel_hi:[1,0,1]
	v_pk_fma_f32 v[84:85], v[208:209], s[28:29], v[84:85] op_sel_hi:[1,0,1]
	v_pk_fma_f32 v[82:83], v[214:215], s[28:29], v[82:83] op_sel_hi:[1,0,1]
	v_pk_fma_f32 v[80:81], v[212:213], s[28:29], v[80:81] op_sel_hi:[1,0,1]
	v_cvt_pk_bf16_f32 v196, v84, v85
	v_cvt_pk_bf16_f32 v197, v86, v87
	v_cvt_pk_bf16_f32 v198, v80, v81
	v_cvt_pk_bf16_f32 v199, v82, v83
	global_store_dwordx4 v[154:155], v[196:199], off
	s_nop 0
	s_nop 0
	v_add_u32_e32 v154, 0xb0, v146
	v_ashrrev_i32_e32 v155, 31, v154
	v_lshlrev_b64 v[154:155], 11, v[154:155]
	v_lshl_add_u64 v[206:207], v[154:155], 0, v[156:157]
	v_lshl_add_u64 v[186:187], v[206:207], 2, s[48:49]
	global_load_dwordx4 v[242:245], v[186:187], off
	global_load_dwordx4 v[246:249], v[186:187], off offset:16
	v_or_b32_e32 v156, 0x80, v156
	v_ashrrev_i32_e32 v157, 31, v156
	v_lshl_add_u64 v[162:163], v[162:163], 0, v[156:157]
	v_lshl_add_u64 v[162:163], v[162:163], 1, s[16:17]
	v_lshl_add_u64 v[160:161], v[160:161], 0, v[156:157]
	v_lshl_add_u64 v[158:159], v[158:159], 0, v[156:157]
	global_load_dwordx4 v[208:211], v[168:169], off offset:512
	global_load_dwordx4 v[212:215], v[168:169], off offset:528
	s_waitcnt vmcnt(5)
	v_pk_fma_f32 v[78:79], v[236:237], s[28:29], v[78:79] op_sel_hi:[1,0,1]
	v_pk_fma_f32 v[76:77], v[234:235], s[28:29], v[76:77] op_sel_hi:[1,0,1]
	v_pk_fma_f32 v[74:75], v[240:241], s[28:29], v[74:75] op_sel_hi:[1,0,1]
	v_pk_fma_f32 v[72:73], v[238:239], s[28:29], v[72:73] op_sel_hi:[1,0,1]
	v_cvt_pk_bf16_f32 v196, v76, v77
	v_cvt_pk_bf16_f32 v197, v78, v79
	v_cvt_pk_bf16_f32 v198, v72, v73
	v_cvt_pk_bf16_f32 v199, v74, v75
	global_store_dwordx4 v[204:205], v[196:199], off
	s_nop 0
	s_nop 0
	v_lshl_add_u64 v[204:205], v[206:207], 1, s[16:17]
	global_load_dwordx4 v[234:237], v[164:165], off offset:512
	global_load_dwordx4 v[238:241], v[164:165], off offset:528
	s_waitcnt vmcnt(5)
	v_pk_fma_f32 v[70:71], v[244:245], s[28:29], v[70:71] op_sel_hi:[1,0,1]
	v_pk_fma_f32 v[68:69], v[242:243], s[28:29], v[68:69] op_sel_hi:[1,0,1]
	v_pk_fma_f32 v[66:67], v[248:249], s[28:29], v[66:67] op_sel_hi:[1,0,1]
	v_pk_fma_f32 v[64:65], v[246:247], s[28:29], v[64:65] op_sel_hi:[1,0,1]
	v_cvt_pk_bf16_f32 v196, v68, v69
	v_cvt_pk_bf16_f32 v197, v70, v71
	v_cvt_pk_bf16_f32 v198, v64, v65
	v_cvt_pk_bf16_f32 v199, v66, v67
	global_store_dwordx4 v[204:205], v[196:199], off
	s_nop 0
	s_nop 0
	v_lshl_add_u64 v[168:169], v[160:161], 1, s[16:17]
	global_load_dwordx4 v[242:245], v[170:171], off offset:512
	global_load_dwordx4 v[246:249], v[170:171], off offset:528
	s_waitcnt vmcnt(6)
	v_pk_fma_f32 v[62:63], v[210:211], s[28:29], v[62:63] op_sel_hi:[1,0,1]
	v_pk_fma_f32 v[60:61], v[208:209], s[28:29], v[60:61] op_sel_hi:[1,0,1]
	v_pk_fma_f32 v[58:59], v[214:215], s[28:29], v[58:59] op_sel_hi:[1,0,1]
	v_pk_fma_f32 v[56:57], v[212:213], s[28:29], v[56:57] op_sel_hi:[1,0,1]
	v_cvt_pk_bf16_f32 v196, v60, v61
	v_cvt_pk_bf16_f32 v197, v62, v63
	v_cvt_pk_bf16_f32 v198, v56, v57
	v_cvt_pk_bf16_f32 v199, v58, v59
	global_store_dwordx4 v[162:163], v[196:199], off
	s_nop 0
	s_nop 0
	s_nop 0
	global_load_dwordx4 v[208:211], v[174:175], off offset:512
	global_load_dwordx4 v[212:215], v[174:175], off offset:528
	s_waitcnt vmcnt(6)
	v_pk_fma_f32 v[54:55], v[236:237], s[28:29], v[54:55] op_sel_hi:[1,0,1]
	v_pk_fma_f32 v[52:53], v[234:235], s[28:29], v[52:53] op_sel_hi:[1,0,1]
	v_pk_fma_f32 v[50:51], v[240:241], s[28:29], v[50:51] op_sel_hi:[1,0,1]
	v_pk_fma_f32 v[48:49], v[238:239], s[28:29], v[48:49] op_sel_hi:[1,0,1]
	v_cvt_pk_bf16_f32 v160, v52, v53
	v_cvt_pk_bf16_f32 v161, v54, v55
	v_cvt_pk_bf16_f32 v162, v48, v49
	v_cvt_pk_bf16_f32 v163, v50, v51
	global_store_dwordx4 v[168:169], v[160:163], off
	s_nop 0
	s_nop 0
	s_nop 0
	v_lshl_add_u64 v[164:165], v[166:167], 0, v[156:157]
	v_lshl_add_u64 v[164:165], v[164:165], 1, s[16:17]
	global_load_dwordx4 v[234:237], v[176:177], off offset:512
	global_load_dwordx4 v[238:241], v[176:177], off offset:528
	s_waitcnt vmcnt(6)
	v_pk_fma_f32 v[46:47], v[244:245], s[28:29], v[46:47] op_sel_hi:[1,0,1]
	v_pk_fma_f32 v[44:45], v[242:243], s[28:29], v[44:45] op_sel_hi:[1,0,1]
	v_pk_fma_f32 v[42:43], v[248:249], s[28:29], v[42:43] op_sel_hi:[1,0,1]
	v_pk_fma_f32 v[40:41], v[246:247], s[28:29], v[40:41] op_sel_hi:[1,0,1]
	v_cvt_pk_bf16_f32 v160, v44, v45
	v_cvt_pk_bf16_f32 v161, v46, v47
	v_cvt_pk_bf16_f32 v162, v40, v41
	v_cvt_pk_bf16_f32 v163, v42, v43
	global_store_dwordx4 v[164:165], v[160:163], off
	s_nop 0
	s_nop 0
	v_lshl_add_u64 v[168:169], v[172:173], 0, v[156:157]
	v_lshl_add_u64 v[168:169], v[168:169], 1, s[16:17]
	global_load_dwordx4 v[242:245], v[180:181], off offset:512
	global_load_dwordx4 v[246:249], v[180:181], off offset:528
	s_waitcnt vmcnt(6)
	v_pk_fma_f32 v[38:39], v[210:211], s[28:29], v[38:39] op_sel_hi:[1,0,1]
	v_pk_fma_f32 v[36:37], v[208:209], s[28:29], v[36:37] op_sel_hi:[1,0,1]
	v_pk_fma_f32 v[34:35], v[214:215], s[28:29], v[34:35] op_sel_hi:[1,0,1]
	v_pk_fma_f32 v[32:33], v[212:213], s[28:29], v[32:33] op_sel_hi:[1,0,1]
	v_cvt_pk_bf16_f32 v160, v36, v37
	v_cvt_pk_bf16_f32 v161, v38, v39
	v_cvt_pk_bf16_f32 v162, v32, v33
	v_cvt_pk_bf16_f32 v163, v34, v35
	global_store_dwordx4 v[168:169], v[160:163], off
	s_nop 0
	s_nop 0
	v_lshl_add_u64 v[168:169], v[158:159], 1, s[16:17]
	global_load_dwordx4 v[208:211], v[184:185], off offset:512
	global_load_dwordx4 v[212:215], v[184:185], off offset:528
	s_waitcnt vmcnt(6)
	v_pk_fma_f32 v[30:31], v[236:237], s[28:29], v[30:31] op_sel_hi:[1,0,1]
	v_pk_fma_f32 v[28:29], v[234:235], s[28:29], v[28:29] op_sel_hi:[1,0,1]
	v_pk_fma_f32 v[26:27], v[240:241], s[28:29], v[26:27] op_sel_hi:[1,0,1]
	v_pk_fma_f32 v[24:25], v[238:239], s[28:29], v[24:25] op_sel_hi:[1,0,1]
	v_cvt_pk_bf16_f32 v158, v28, v29
	v_cvt_pk_bf16_f32 v159, v30, v31
	v_cvt_pk_bf16_f32 v160, v24, v25
	v_cvt_pk_bf16_f32 v161, v26, v27
	global_store_dwordx4 v[168:169], v[158:161], off
	s_nop 0
	s_nop 0
	v_lshl_add_u64 v[166:167], v[178:179], 0, v[156:157]
	v_lshl_add_u64 v[166:167], v[166:167], 1, s[16:17]
	v_add_f32_e32 v168, v152, v153
	v_add_f32_e32 v169, v126, v127
	v_mul_f32_e32 v153, v153, v153
	v_mul_f32_e32 v127, v127, v127
	v_fmac_f32_e32 v153, v152, v152
	v_fmac_f32_e32 v127, v126, v126
	v_add_f32_e32 v127, v153, v127
	s_waitcnt vmcnt(4)
	v_pk_fma_f32 v[22:23], v[244:245], s[28:29], v[22:23] op_sel_hi:[1,0,1]
	v_pk_fma_f32 v[20:21], v[242:243], s[28:29], v[20:21] op_sel_hi:[1,0,1]
	v_pk_fma_f32 v[18:19], v[248:249], s[28:29], v[18:19] op_sel_hi:[1,0,1]
	v_pk_fma_f32 v[16:17], v[246:247], s[28:29], v[16:17] op_sel_hi:[1,0,1]
	v_cvt_pk_bf16_f32 v158, v20, v21
	v_cvt_pk_bf16_f32 v159, v22, v23
	v_cvt_pk_bf16_f32 v160, v16, v17
	v_cvt_pk_bf16_f32 v161, v18, v19
	global_store_dwordx4 v[166:167], v[158:161], off
	s_nop 0
	s_nop 0
	v_lshl_add_u64 v[166:167], v[182:183], 0, v[156:157]
	v_lshl_add_u64 v[166:167], v[166:167], 1, s[16:17]
	s_waitcnt vmcnt(2)
	v_pk_fma_f32 v[14:15], v[210:211], s[28:29], v[14:15] op_sel_hi:[1,0,1]
	v_pk_fma_f32 v[12:13], v[208:209], s[28:29], v[12:13] op_sel_hi:[1,0,1]
	v_pk_fma_f32 v[10:11], v[214:215], s[28:29], v[10:11] op_sel_hi:[1,0,1]
	v_pk_fma_f32 v[8:9], v[212:213], s[28:29], v[8:9] op_sel_hi:[1,0,1]
	v_cvt_pk_bf16_f32 v158, v12, v13
	v_cvt_pk_bf16_f32 v159, v14, v15
	v_cvt_pk_bf16_f32 v160, v8, v9
	v_cvt_pk_bf16_f32 v161, v10, v11
	global_store_dwordx4 v[166:167], v[158:161], off
	global_load_dwordx4 v[158:161], v[186:187], off offset:512
	global_load_dwordx4 v[162:165], v[186:187], off offset:528
	v_add_f32_e32 v166, v150, v151
	v_add_f32_e32 v167, v148, v149
	v_mul_f32_e32 v151, v151, v151
	v_mul_f32_e32 v149, v149, v149
	v_fmac_f32_e32 v151, v150, v150
	v_fmac_f32_e32 v149, v148, v148
	v_add_f32_e32 v148, v151, v149
	v_add_f32_e32 v166, v166, v167
	v_add_f32_e32 v167, v168, v169
	v_add_f32_e32 v127, v148, v127
	v_add_f32_e32 v148, v60, v61
	v_add_f32_e32 v149, v62, v63
	v_add_f32_e32 v150, v56, v57
	v_add_f32_e32 v151, v58, v59
	v_mul_f32_e32 v61, v61, v61
	v_mul_f32_e32 v63, v63, v63
	v_mul_f32_e32 v57, v57, v57
	v_mul_f32_e32 v59, v59, v59
	v_add_f32_e32 v126, v166, v167
	v_add_f32_e32 v148, v148, v149
	v_add_f32_e32 v149, v150, v151
	v_fmac_f32_e32 v61, v60, v60
	v_fmac_f32_e32 v63, v62, v62
	v_fmac_f32_e32 v57, v56, v56
	v_fmac_f32_e32 v59, v58, v58
	v_add_f32_e32 v126, 0, v126
	v_add_f32_e32 v56, v148, v149
	v_add_f32_e32 v58, v61, v63
	v_add_f32_e32 v57, v57, v59
	v_add_f32_e32 v59, v126, v56
	v_add_f32_e32 v56, v58, v57
	v_add_f32_e32 v60, v127, v56
	ds_bpermute_b32 v58, v190, v59
	ds_bpermute_b32 v61, v190, v60
	v_lshl_add_u64 v[56:57], v[154:155], 0, v[156:157]
	v_lshl_add_u64 v[126:127], v[56:57], 1, s[16:17]
	s_waitcnt lgkmcnt(0)
	v_add_f32_e32 v56, v59, v58
	v_add_f32_e32 v58, v60, v61
	ds_bpermute_b32 v57, v191, v56
	ds_bpermute_b32 v59, v191, v58
	s_waitcnt vmcnt(1)
	v_pk_fma_f32 v[6:7], v[160:161], s[28:29], v[6:7] op_sel_hi:[1,0,1]
	v_pk_fma_f32 v[4:5], v[158:159], s[28:29], v[4:5] op_sel_hi:[1,0,1]
	s_waitcnt vmcnt(0)
	v_pk_fma_f32 v[2:3], v[164:165], s[28:29], v[2:3] op_sel_hi:[1,0,1]
	v_pk_fma_f32 v[0:1], v[162:163], s[28:29], v[0:1] op_sel_hi:[1,0,1]
	v_cvt_pk_bf16_f32 v60, v4, v5
	v_cvt_pk_bf16_f32 v61, v6, v7
	v_cvt_pk_bf16_f32 v62, v0, v1
	v_cvt_pk_bf16_f32 v63, v2, v3
	global_store_dwordx4 v[126:127], v[60:63], off
	s_and_saveexec_b64 s[34:35], s[6:7]
	s_cbranch_execz .LBB0_680
	s_waitcnt lgkmcnt(0)
	v_add_f32_e32 v58, v58, v59
	v_add_f32_e32 v59, v56, v57
	v_lshl_add_u64 v[56:57], v[146:147], 3, s[20:21]
	global_atomic_add_f32 v[56:57], v59, off
	global_atomic_add_f32 v[56:57], v58, off offset:4

.LBB0_1295:
	v_lshl_add_u32 v128, s79, 8, v223
	v_ashrrev_i32_e32 v129, 31, v128
	v_lshlrev_b64 v[164:165], 3, v[128:129]
	v_lshl_add_u64 v[130:131], s[14:15], 0, v[164:165]
	global_load_dwordx2 v[186:187], v[130:131], off
	v_lshl_or_b32 v130, s78, 8, v225
	v_ashrrev_i32_e32 v131, 31, v130
	v_lshlrev_b64 v[132:133], 12, v[128:129]
	v_lshl_add_u64 v[132:133], s[16:17], 0, v[132:133]
	v_lshlrev_b64 v[178:179], 1, v[130:131]
	v_lshl_add_u64 v[176:177], v[132:133], 0, v[178:179]
	global_load_dwordx4 v[192:195], v[176:177], off
	v_or_b32_e32 v196, 16, v128
	v_or_b32_e32 v218, 32, v128
	v_or_b32_e32 v198, 48, v128
	v_add_u32_e32 v204, 0x80, v128
	v_add_u32_e32 v208, 0x90, v128
	v_add_u32_e32 v184, 0xa0, v128
	v_add_u32_e32 v180, 0xb0, v128
	v_lshlrev_b64 v[128:129], 2, v[130:131]
	v_lshl_add_u64 v[188:189], s[68:69], 0, v[128:129]
	v_lshl_add_u64 v[190:191], s[70:71], 0, v[128:129]
	global_load_dwordx4 v[128:131], v[188:189], off offset:16
	global_load_dwordx4 v[136:139], v[188:189], off
	global_load_dwordx4 v[132:135], v[190:191], off offset:16
	global_load_dwordx4 v[140:143], v[190:191], off
	v_ashrrev_i32_e32 v197, 31, v196
	v_ashrrev_i32_e32 v219, 31, v218
	v_ashrrev_i32_e32 v199, 31, v198
	v_ashrrev_i32_e32 v205, 31, v204
	v_ashrrev_i32_e32 v209, 31, v208
	v_ashrrev_i32_e32 v185, 31, v184
	v_ashrrev_i32_e32 v181, 31, v180
	v_lshlrev_b64 v[174:175], 3, v[196:197]
	v_lshlrev_b64 v[172:173], 3, v[218:219]
	v_lshlrev_b64 v[170:171], 3, v[198:199]
	v_lshlrev_b64 v[168:169], 3, v[204:205]
	v_lshlrev_b64 v[166:167], 3, v[208:209]
	v_lshlrev_b64 v[162:163], 3, v[184:185]
	v_lshlrev_b64 v[160:161], 3, v[180:181]
	v_lshl_add_u64 v[182:183], s[14:15], 0, v[174:175]
	v_lshl_add_u64 v[200:201], s[14:15], 0, v[172:173]
	v_lshl_add_u64 v[202:203], s[14:15], 0, v[170:171]
	v_lshl_add_u64 v[210:211], s[14:15], 0, v[168:169]
	v_lshl_add_u64 v[212:213], s[14:15], 0, v[166:167]
	v_lshl_add_u64 v[214:215], s[14:15], 0, v[162:163]
	v_lshl_add_u64 v[216:217], s[14:15], 0, v[160:161]
	global_load_dwordx2 v[230:231], v[182:183], off
	s_nop 0
	global_load_dwordx2 v[200:201], v[200:201], off
	s_nop 0
	global_load_dwordx2 v[206:207], v[202:203], off
	s_nop 0
	global_load_dwordx2 v[210:211], v[210:211], off
	s_nop 0
	global_load_dwordx2 v[212:213], v[212:213], off
	s_nop 0
	global_load_dwordx2 v[182:183], v[214:215], off
	global_load_dwordx2 v[202:203], v[216:217], off
	v_lshlrev_b64 v[198:199], 12, v[198:199]
	v_lshl_add_u64 v[198:199], s[16:17], 0, v[198:199]
	v_lshl_add_u64 v[198:199], v[198:199], 0, v[178:179]
	v_lshlrev_b64 v[204:205], 12, v[204:205]
	v_lshl_add_u64 v[204:205], s[16:17], 0, v[204:205]
	v_lshl_add_u64 v[204:205], v[204:205], 0, v[178:179]
	v_lshlrev_b64 v[208:209], 12, v[208:209]
	v_lshl_add_u64 v[208:209], s[16:17], 0, v[208:209]
	v_lshl_add_u64 v[208:209], v[208:209], 0, v[178:179]
	v_lshlrev_b64 v[184:185], 12, v[184:185]
	v_lshl_add_u64 v[184:185], s[16:17], 0, v[184:185]
	v_lshlrev_b64 v[180:181], 12, v[180:181]
	v_lshl_add_u64 v[180:181], s[16:17], 0, v[180:181]
	s_waitcnt vmcnt(0)
	v_pk_mul_f32 v[186:187], v[186:187], s[30:31] op_sel:[1,0] op_sel_hi:[0,0]
	v_fma_f32 v186, -v187, v187, v186
	v_max_f32_e32 v186, 0, v186
	v_add_f32_e32 v186, 0x3727c5ac, v186
	v_cmp_gt_f32_e32 vcc, s63, v186
	v_lshlrev_b32_e32 v214, 16, v192
	v_and_b32_e32 v192, 0xffff0000, v192
	v_lshlrev_b32_e32 v215, 16, v193
	v_and_b32_e32 v216, 0xffff0000, v193
	v_sub_f32_e32 v193, v192, v187
	v_sub_f32_e32 v192, v214, v187
	v_mul_f32_e32 v214, 0x4f800000, v186
	v_cndmask_b32_e32 v186, v186, v214, vcc
	v_lshlrev_b32_e32 v233, 16, v195
	v_and_b32_e32 v234, 0xffff0000, v195
	v_sub_f32_e32 v195, v216, v187
	v_sqrt_f32_e32 v216, v186
	v_and_b32_e32 v232, 0xffff0000, v194
	v_lshlrev_b32_e32 v217, 16, v194
	v_sub_f32_e32 v194, v215, v187
	v_sub_f32_e32 v215, v232, v187
	v_add_u32_e32 v232, -1, v216
	v_sub_f32_e32 v214, v217, v187
	v_sub_f32_e32 v217, v234, v187
	v_add_u32_e32 v234, 1, v216
	v_fma_f32 v235, -v232, v216, v186
	v_fma_f32 v236, -v234, v216, v186
	v_cmp_ge_f32_e64 s[0:1], 0, v235
	v_pk_mul_f32 v[200:201], v[200:201], s[30:31] op_sel:[1,0] op_sel_hi:[0,0]
	s_nop 0
	v_cndmask_b32_e64 v216, v216, v232, s[0:1]
	v_cmp_lt_f32_e64 s[0:1], 0, v236
	v_fma_f32 v200, -v201, v201, v200
	v_max_f32_e32 v200, 0, v200
	v_cndmask_b32_e64 v216, v216, v234, s[0:1]
	v_mul_f32_e32 v232, 0x37800000, v216
	v_cndmask_b32_e32 v216, v216, v232, vcc
	v_cmp_class_f32_e32 vcc, v186, v229
	v_add_f32_e32 v200, 0x3727c5ac, v200
	v_pk_mul_f32 v[206:207], v[206:207], s[30:31] op_sel:[1,0] op_sel_hi:[0,0]
	v_cndmask_b32_e32 v186, v216, v186, vcc
	v_div_scale_f32 v232, s[0:1], v186, v186, 1.0
	v_rcp_f32_e32 v234, v232
	v_sub_f32_e32 v216, v233, v187
	v_div_scale_f32 v233, vcc, 1.0, v186, 1.0
	v_fma_f32 v235, -v232, v234, 1.0
	v_fmac_f32_e32 v234, v235, v234
	v_mul_f32_e32 v235, v233, v234
	v_fma_f32 v236, -v232, v235, v233
	v_fmac_f32_e32 v235, v236, v234
	v_fma_f32 v232, -v232, v235, v233
	v_div_fmas_f32 v232, v232, v234, v235
	v_div_fixup_f32 v186, v232, v186, 1.0
	v_pk_mul_f32 v[194:195], v[186:187], v[194:195] op_sel_hi:[0,1]
	v_pk_mul_f32 v[192:193], v[186:187], v[192:193] op_sel_hi:[0,1]
	v_pk_mul_f32 v[216:217], v[186:187], v[216:217] op_sel_hi:[0,1]
	v_pk_mul_f32 v[214:215], v[186:187], v[214:215] op_sel_hi:[0,1]
	v_pk_fma_f32 v[192:193], v[136:137], v[192:193], v[140:141]
	v_pk_fma_f32 v[194:195], v[138:139], v[194:195], v[142:143]
	v_pk_fma_f32 v[214:215], v[128:129], v[214:215], v[132:133]
	v_pk_fma_f32 v[216:217], v[130:131], v[216:217], v[134:135]
	v_pk_fma_f32 v[126:127], v[194:195], s[34:35], v[126:127] op_sel_hi:[1,0,1]
	v_pk_fma_f32 v[124:125], v[192:193], s[34:35], v[124:125] op_sel_hi:[1,0,1]
	v_pk_fma_f32 v[122:123], v[216:217], s[34:35], v[122:123] op_sel_hi:[1,0,1]
	v_pk_fma_f32 v[120:121], v[214:215], s[34:35], v[120:121] op_sel_hi:[1,0,1]
	v_cvt_pk_bf16_f32 v192, v124, v125
	v_cvt_pk_bf16_f32 v193, v126, v127
	v_cvt_pk_bf16_f32 v194, v120, v121
	v_cvt_pk_bf16_f32 v195, v122, v123
	global_store_dwordx4 v[176:177], v[192:195], off
	v_fma_f32 v206, -v207, v207, v206
	v_max_f32_e32 v206, 0, v206
	v_lshlrev_b64 v[192:193], 12, v[196:197]
	v_lshl_add_u64 v[192:193], s[16:17], 0, v[192:193]
	v_lshl_add_u64 v[192:193], v[192:193], 0, v[178:179]
	global_load_dwordx4 v[238:241], v[192:193], off
	v_pk_mul_f32 v[196:197], v[230:231], s[30:31] op_sel:[1,0] op_sel_hi:[0,0]
	v_fma_f32 v194, -v197, v197, v196
	v_max_f32_e32 v194, 0, v194
	v_add_f32_e32 v194, 0x3727c5ac, v194
	v_mul_f32_e32 v195, 0x4f800000, v194
	v_cmp_gt_f32_e32 vcc, s63, v194
	v_add_f32_e32 v206, 0x3727c5ac, v206
	v_pk_mul_f32 v[210:211], v[210:211], s[30:31] op_sel:[1,0] op_sel_hi:[0,0]
	v_cndmask_b32_e32 v196, v194, v195, vcc
	v_sqrt_f32_e32 v230, v196
	v_lshlrev_b64 v[194:195], 12, v[218:219]
	v_lshl_add_u64 v[194:195], s[16:17], 0, v[194:195]
	v_lshl_add_u64 v[194:195], v[194:195], 0, v[178:179]
	v_add_u32_e32 v218, -1, v230
	v_add_u32_e32 v219, 1, v230
	v_fma_f32 v231, -v218, v230, v196
	v_fma_f32 v232, -v219, v230, v196
	v_cmp_ge_f32_e64 s[0:1], 0, v231
	v_fma_f32 v210, -v211, v211, v210
	v_max_f32_e32 v210, 0, v210
	v_cndmask_b32_e64 v218, v230, v218, s[0:1]
	v_cmp_lt_f32_e64 s[0:1], 0, v232
	v_add_f32_e32 v210, 0x3727c5ac, v210
	v_pk_mul_f32 v[202:203], v[202:203], s[30:31] op_sel:[1,0] op_sel_hi:[0,0]
	v_cndmask_b32_e64 v218, v218, v219, s[0:1]
	v_mul_f32_e32 v219, 0x37800000, v218
	v_cndmask_b32_e32 v218, v218, v219, vcc
	v_cmp_class_f32_e32 vcc, v196, v229
	global_load_dwordx4 v[246:249], v[198:199], off
	global_load_dwordx4 v[242:245], v[194:195], off
	s_waitcnt vmcnt(2)
	v_lshlrev_b32_e32 v233, 16, v241
	v_cndmask_b32_e32 v196, v218, v196, vcc
	v_div_scale_f32 v218, s[0:1], v196, v196, 1.0
	v_rcp_f32_e32 v219, v218
	v_div_scale_f32 v230, vcc, 1.0, v196, 1.0
	v_and_b32_e32 v234, 0xffff0000, v241
	v_fma_f32 v231, -v218, v219, 1.0
	v_fmac_f32_e32 v219, v231, v219
	v_mul_f32_e32 v231, v230, v219
	v_fma_f32 v232, -v218, v231, v230
	v_fmac_f32_e32 v231, v232, v219
	v_fma_f32 v218, -v218, v231, v230
	v_div_fmas_f32 v218, v218, v219, v231
	v_div_fixup_f32 v196, v218, v196, 1.0
	v_lshlrev_b32_e32 v218, 16, v238
	v_and_b32_e32 v214, 0xffff0000, v238
	v_lshlrev_b32_e32 v219, 16, v239
	v_and_b32_e32 v230, 0xffff0000, v239
	v_lshlrev_b32_e32 v231, 16, v240
	v_and_b32_e32 v232, 0xffff0000, v240
	v_sub_f32_e32 v215, v214, v197
	v_sub_f32_e32 v214, v218, v197
	v_sub_f32_e32 v217, v230, v197
	v_sub_f32_e32 v216, v219, v197
	v_sub_f32_e32 v219, v232, v197
	v_sub_f32_e32 v218, v231, v197
	v_sub_f32_e32 v231, v234, v197
	v_sub_f32_e32 v230, v233, v197
	v_pk_mul_f32 v[216:217], v[196:197], v[216:217] op_sel_hi:[0,1]
	v_pk_mul_f32 v[214:215], v[196:197], v[214:215] op_sel_hi:[0,1]
	v_pk_mul_f32 v[230:231], v[196:197], v[230:231] op_sel_hi:[0,1]
	v_pk_mul_f32 v[218:219], v[196:197], v[218:219] op_sel_hi:[0,1]
	v_pk_fma_f32 v[214:215], v[136:137], v[214:215], v[140:141]
	v_pk_fma_f32 v[216:217], v[138:139], v[216:217], v[142:143]
	v_pk_fma_f32 v[218:219], v[128:129], v[218:219], v[132:133]
	v_pk_fma_f32 v[230:231], v[130:131], v[230:231], v[134:135]
	v_pk_fma_f32 v[118:119], v[216:217], s[34:35], v[118:119] op_sel_hi:[1,0,1]
	v_pk_fma_f32 v[116:117], v[214:215], s[34:35], v[116:117] op_sel_hi:[1,0,1]
	v_pk_fma_f32 v[114:115], v[230:231], s[34:35], v[114:115] op_sel_hi:[1,0,1]
	v_pk_fma_f32 v[112:113], v[218:219], s[34:35], v[112:113] op_sel_hi:[1,0,1]
	v_cvt_pk_bf16_f32 v214, v116, v117
	v_cvt_pk_bf16_f32 v215, v118, v119
	v_cvt_pk_bf16_f32 v216, v112, v113
	v_cvt_pk_bf16_f32 v217, v114, v115
	global_store_dwordx4 v[192:193], v[214:217], off
	s_nop 0
	v_mul_f32_e32 v218, 0x4f800000, v200
	v_cmp_gt_f32_e32 vcc, s63, v200
	global_load_dwordx4 v[238:241], v[204:205], off
	s_waitcnt vmcnt(2)
	v_lshlrev_b32_e32 v233, 16, v245
	v_cndmask_b32_e32 v200, v200, v218, vcc
	v_sqrt_f32_e32 v218, v200
	v_and_b32_e32 v234, 0xffff0000, v245
	v_add_u32_e32 v219, -1, v218
	v_add_u32_e32 v230, 1, v218
	v_fma_f32 v231, -v219, v218, v200
	v_fma_f32 v232, -v230, v218, v200
	v_cmp_ge_f32_e64 s[0:1], 0, v231
	s_nop 1
	v_cndmask_b32_e64 v218, v218, v219, s[0:1]
	v_cmp_lt_f32_e64 s[0:1], 0, v232
	s_nop 1
	v_cndmask_b32_e64 v218, v218, v230, s[0:1]
	v_mul_f32_e32 v219, 0x37800000, v218
	v_cndmask_b32_e32 v218, v218, v219, vcc
	v_cmp_class_f32_e32 vcc, v200, v229
	s_nop 1
	v_cndmask_b32_e32 v200, v218, v200, vcc
	v_div_scale_f32 v218, s[0:1], v200, v200, 1.0
	v_rcp_f32_e32 v219, v218
	v_div_scale_f32 v230, vcc, 1.0, v200, 1.0
	v_fma_f32 v231, -v218, v219, 1.0
	v_fmac_f32_e32 v219, v231, v219
	v_mul_f32_e32 v231, v230, v219
	v_fma_f32 v232, -v218, v231, v230
	v_fmac_f32_e32 v231, v232, v219
	v_fma_f32 v218, -v218, v231, v230
	v_div_fmas_f32 v218, v218, v219, v231
	v_div_fixup_f32 v200, v218, v200, 1.0
	v_lshlrev_b32_e32 v218, 16, v242
	v_and_b32_e32 v214, 0xffff0000, v242
	v_lshlrev_b32_e32 v219, 16, v243
	v_and_b32_e32 v230, 0xffff0000, v243
	v_lshlrev_b32_e32 v231, 16, v244
	v_and_b32_e32 v232, 0xffff0000, v244
	v_sub_f32_e32 v215, v214, v201
	v_sub_f32_e32 v214, v218, v201
	v_sub_f32_e32 v217, v230, v201
	v_sub_f32_e32 v216, v219, v201
	v_sub_f32_e32 v219, v232, v201
	v_sub_f32_e32 v218, v231, v201
	v_sub_f32_e32 v231, v234, v201
	v_sub_f32_e32 v230, v233, v201
	v_pk_mul_f32 v[216:217], v[200:201], v[216:217] op_sel_hi:[0,1]
	v_pk_mul_f32 v[214:215], v[200:201], v[214:215] op_sel_hi:[0,1]
	v_pk_mul_f32 v[230:231], v[200:201], v[230:231] op_sel_hi:[0,1]
	v_pk_mul_f32 v[218:219], v[200:201], v[218:219] op_sel_hi:[0,1]
	v_pk_fma_f32 v[214:215], v[136:137], v[214:215], v[140:141]
	v_pk_fma_f32 v[216:217], v[138:139], v[216:217], v[142:143]
	v_pk_fma_f32 v[218:219], v[128:129], v[218:219], v[132:133]
	v_pk_fma_f32 v[230:231], v[130:131], v[230:231], v[134:135]
	v_pk_fma_f32 v[110:111], v[216:217], s[34:35], v[110:111] op_sel_hi:[1,0,1]
	v_pk_fma_f32 v[108:109], v[214:215], s[34:35], v[108:109] op_sel_hi:[1,0,1]
	v_pk_fma_f32 v[106:107], v[230:231], s[34:35], v[106:107] op_sel_hi:[1,0,1]
	v_pk_fma_f32 v[104:105], v[218:219], s[34:35], v[104:105] op_sel_hi:[1,0,1]
	v_cvt_pk_bf16_f32 v214, v108, v109
	v_cvt_pk_bf16_f32 v215, v110, v111
	v_cvt_pk_bf16_f32 v216, v104, v105
	v_cvt_pk_bf16_f32 v217, v106, v107
	global_store_dwordx4 v[194:195], v[214:217], off
	s_nop 0
	v_mul_f32_e32 v218, 0x4f800000, v206
	v_cmp_gt_f32_e32 vcc, s63, v206
	global_load_dwordx4 v[242:245], v[208:209], off
	s_waitcnt vmcnt(5)
	v_lshlrev_b32_e32 v233, 16, v249
	v_cndmask_b32_e32 v206, v206, v218, vcc
	v_sqrt_f32_e32 v218, v206
	v_and_b32_e32 v234, 0xffff0000, v249
	v_add_u32_e32 v219, -1, v218
	v_add_u32_e32 v230, 1, v218
	v_fma_f32 v231, -v219, v218, v206
	v_fma_f32 v232, -v230, v218, v206
	v_cmp_ge_f32_e64 s[0:1], 0, v231
	s_nop 1
	v_cndmask_b32_e64 v218, v218, v219, s[0:1]
	v_cmp_lt_f32_e64 s[0:1], 0, v232
	s_nop 1
	v_cndmask_b32_e64 v218, v218, v230, s[0:1]
	v_mul_f32_e32 v219, 0x37800000, v218
	v_cndmask_b32_e32 v218, v218, v219, vcc
	v_cmp_class_f32_e32 vcc, v206, v229
	s_nop 1
	v_cndmask_b32_e32 v206, v218, v206, vcc
	v_div_scale_f32 v218, s[0:1], v206, v206, 1.0
	v_rcp_f32_e32 v219, v218
	v_div_scale_f32 v230, vcc, 1.0, v206, 1.0
	v_fma_f32 v231, -v218, v219, 1.0
	v_fmac_f32_e32 v219, v231, v219
	v_mul_f32_e32 v231, v230, v219
	v_fma_f32 v232, -v218, v231, v230
	v_fmac_f32_e32 v231, v232, v219
	v_fma_f32 v218, -v218, v231, v230
	v_div_fmas_f32 v218, v218, v219, v231
	v_div_fixup_f32 v206, v218, v206, 1.0
	v_lshlrev_b32_e32 v218, 16, v246
	v_and_b32_e32 v214, 0xffff0000, v246
	v_lshlrev_b32_e32 v219, 16, v247
	v_and_b32_e32 v230, 0xffff0000, v247
	v_lshlrev_b32_e32 v231, 16, v248
	v_and_b32_e32 v232, 0xffff0000, v248
	v_sub_f32_e32 v215, v214, v207
	v_sub_f32_e32 v214, v218, v207
	v_sub_f32_e32 v217, v230, v207
	v_sub_f32_e32 v216, v219, v207
	v_sub_f32_e32 v219, v232, v207
	v_sub_f32_e32 v218, v231, v207
	v_sub_f32_e32 v231, v234, v207
	v_sub_f32_e32 v230, v233, v207
	v_pk_mul_f32 v[216:217], v[206:207], v[216:217] op_sel_hi:[0,1]
	v_pk_mul_f32 v[214:215], v[206:207], v[214:215] op_sel_hi:[0,1]
	v_pk_mul_f32 v[230:231], v[206:207], v[230:231] op_sel_hi:[0,1]
	v_pk_mul_f32 v[218:219], v[206:207], v[218:219] op_sel_hi:[0,1]
	v_pk_fma_f32 v[214:215], v[136:137], v[214:215], v[140:141]
	v_pk_fma_f32 v[216:217], v[138:139], v[216:217], v[142:143]
	v_pk_fma_f32 v[218:219], v[128:129], v[218:219], v[132:133]
	v_pk_fma_f32 v[230:231], v[130:131], v[230:231], v[134:135]
	v_pk_fma_f32 v[102:103], v[216:217], s[34:35], v[102:103] op_sel_hi:[1,0,1]
	v_pk_fma_f32 v[100:101], v[214:215], s[34:35], v[100:101] op_sel_hi:[1,0,1]
	v_pk_fma_f32 v[98:99], v[230:231], s[34:35], v[98:99] op_sel_hi:[1,0,1]
	v_pk_fma_f32 v[96:97], v[218:219], s[34:35], v[96:97] op_sel_hi:[1,0,1]
	v_cvt_pk_bf16_f32 v214, v100, v101
	v_cvt_pk_bf16_f32 v215, v102, v103
	v_cvt_pk_bf16_f32 v216, v96, v97
	v_cvt_pk_bf16_f32 v217, v98, v99
	global_store_dwordx4 v[198:199], v[214:217], off
	s_nop 0
	v_mul_f32_e32 v218, 0x4f800000, v210
	v_cmp_gt_f32_e32 vcc, s63, v210
	s_waitcnt vmcnt(3)
	v_lshlrev_b32_e32 v233, 16, v241
	v_cndmask_b32_e32 v210, v210, v218, vcc
	v_sqrt_f32_e32 v218, v210
	v_and_b32_e32 v234, 0xffff0000, v241
	v_add_u32_e32 v219, -1, v218
	v_add_u32_e32 v230, 1, v218
	v_fma_f32 v231, -v219, v218, v210
	v_fma_f32 v232, -v230, v218, v210
	v_cmp_ge_f32_e64 s[0:1], 0, v231
	s_nop 1
	v_cndmask_b32_e64 v218, v218, v219, s[0:1]
	v_cmp_lt_f32_e64 s[0:1], 0, v232
	s_nop 1
	v_cndmask_b32_e64 v218, v218, v230, s[0:1]
	v_mul_f32_e32 v219, 0x37800000, v218
	v_cndmask_b32_e32 v218, v218, v219, vcc
	v_cmp_class_f32_e32 vcc, v210, v229
	s_nop 1
	v_cndmask_b32_e32 v210, v218, v210, vcc
	v_div_scale_f32 v218, s[0:1], v210, v210, 1.0
	v_rcp_f32_e32 v219, v218
	v_div_scale_f32 v230, vcc, 1.0, v210, 1.0
	v_fma_f32 v231, -v218, v219, 1.0
	v_fmac_f32_e32 v219, v231, v219
	v_mul_f32_e32 v231, v230, v219
	v_fma_f32 v232, -v218, v231, v230
	v_fmac_f32_e32 v231, v232, v219
	v_fma_f32 v218, -v218, v231, v230
	v_div_fmas_f32 v218, v218, v219, v231
	v_div_fixup_f32 v210, v218, v210, 1.0
	v_lshlrev_b32_e32 v218, 16, v238
	v_and_b32_e32 v214, 0xffff0000, v238
	v_lshlrev_b32_e32 v219, 16, v239
	v_and_b32_e32 v230, 0xffff0000, v239
	v_lshlrev_b32_e32 v231, 16, v240
	v_and_b32_e32 v232, 0xffff0000, v240
	v_sub_f32_e32 v215, v214, v211
	v_sub_f32_e32 v214, v218, v211
	v_sub_f32_e32 v217, v230, v211
	v_sub_f32_e32 v216, v219, v211
	v_sub_f32_e32 v219, v232, v211
	v_sub_f32_e32 v218, v231, v211
	v_sub_f32_e32 v231, v234, v211
	v_sub_f32_e32 v230, v233, v211
	v_pk_mul_f32 v[216:217], v[210:211], v[216:217] op_sel_hi:[0,1]
	v_pk_mul_f32 v[214:215], v[210:211], v[214:215] op_sel_hi:[0,1]
	v_pk_mul_f32 v[230:231], v[210:211], v[230:231] op_sel_hi:[0,1]
	v_pk_mul_f32 v[218:219], v[210:211], v[218:219] op_sel_hi:[0,1]
	v_pk_fma_f32 v[214:215], v[136:137], v[214:215], v[140:141]
	v_pk_fma_f32 v[216:217], v[138:139], v[216:217], v[142:143]
	v_pk_fma_f32 v[218:219], v[128:129], v[218:219], v[132:133]
	v_pk_fma_f32 v[230:231], v[130:131], v[230:231], v[134:135]
	v_pk_fma_f32 v[94:95], v[216:217], s[34:35], v[94:95] op_sel_hi:[1,0,1]
	v_pk_fma_f32 v[92:93], v[214:215], s[34:35], v[92:93] op_sel_hi:[1,0,1]
	v_pk_fma_f32 v[90:91], v[230:231], s[34:35], v[90:91] op_sel_hi:[1,0,1]
	v_pk_fma_f32 v[88:89], v[218:219], s[34:35], v[88:89] op_sel_hi:[1,0,1]
	v_cvt_pk_bf16_f32 v214, v92, v93
	v_cvt_pk_bf16_f32 v215, v94, v95
	v_cvt_pk_bf16_f32 v216, v88, v89
	v_cvt_pk_bf16_f32 v217, v90, v91
	global_store_dwordx4 v[204:205], v[214:217], off
	s_nop 0
	s_waitcnt vmcnt(2)
	v_and_b32_e32 v219, 0xffff0000, v244
	v_pk_mul_f32 v[216:217], v[212:213], s[30:31] op_sel:[1,0] op_sel_hi:[0,0]
	v_fma_f32 v212, -v217, v217, v216
	v_max_f32_e32 v212, 0, v212
	v_add_f32_e32 v212, 0x3727c5ac, v212
	v_mul_f32_e32 v213, 0x4f800000, v212
	v_cmp_gt_f32_e32 vcc, s63, v212
	v_sub_f32_e32 v219, v219, v217
	s_nop 0
	v_cndmask_b32_e32 v212, v212, v213, vcc
	v_sqrt_f32_e32 v213, v212
	s_nop 0
	v_add_u32_e32 v214, -1, v213
	v_add_u32_e32 v215, 1, v213
	v_fma_f32 v216, -v214, v213, v212
	v_fma_f32 v218, -v215, v213, v212
	v_cmp_ge_f32_e64 s[0:1], 0, v216
	s_nop 1
	v_cndmask_b32_e64 v213, v213, v214, s[0:1]
	v_cmp_lt_f32_e64 s[0:1], 0, v218
	s_nop 1
	v_cndmask_b32_e64 v213, v213, v215, s[0:1]
	v_mul_f32_e32 v214, 0x37800000, v213
	v_cndmask_b32_e32 v213, v213, v214, vcc
	v_cmp_class_f32_e32 vcc, v212, v229
	v_lshl_add_u64 v[214:215], v[184:185], 0, v[178:179]
	global_load_dwordx4 v[246:249], v[214:215], off
	s_nop 0
	v_cndmask_b32_e32 v212, v213, v212, vcc
	v_div_scale_f32 v213, s[0:1], v212, v212, 1.0
	v_rcp_f32_e32 v216, v213
	v_div_scale_f32 v184, vcc, 1.0, v212, 1.0
	v_fma_f32 v185, -v213, v216, 1.0
	v_fmac_f32_e32 v216, v185, v216
	v_mul_f32_e32 v185, v184, v216
	v_fma_f32 v218, -v213, v185, v184
	v_fmac_f32_e32 v185, v218, v216
	v_fma_f32 v184, -v213, v185, v184
	v_div_fmas_f32 v184, v184, v216, v185
	v_div_fixup_f32 v216, v184, v212, 1.0
	v_lshlrev_b32_e32 v184, 16, v242
	v_and_b32_e32 v185, 0xffff0000, v242
	v_lshlrev_b32_e32 v212, 16, v243
	v_and_b32_e32 v213, 0xffff0000, v243
	v_lshlrev_b32_e32 v218, 16, v244
	v_lshlrev_b32_e32 v230, 16, v245
	v_and_b32_e32 v231, 0xffff0000, v245
	v_sub_f32_e32 v185, v185, v217
	v_sub_f32_e32 v184, v184, v217
	v_sub_f32_e32 v213, v213, v217
	v_sub_f32_e32 v212, v212, v217
	v_sub_f32_e32 v218, v218, v217
	v_sub_f32_e32 v231, v231, v217
	v_sub_f32_e32 v230, v230, v217
	v_pk_mul_f32 v[212:213], v[216:217], v[212:213] op_sel_hi:[0,1]
	v_pk_mul_f32 v[184:185], v[216:217], v[184:185] op_sel_hi:[0,1]
	v_pk_mul_f32 v[230:231], v[216:217], v[230:231] op_sel_hi:[0,1]
	v_pk_mul_f32 v[218:219], v[216:217], v[218:219] op_sel_hi:[0,1]
	v_pk_fma_f32 v[184:185], v[136:137], v[184:185], v[140:141]
	v_pk_fma_f32 v[212:213], v[138:139], v[212:213], v[142:143]
	v_pk_fma_f32 v[218:219], v[128:129], v[218:219], v[132:133]
	v_pk_fma_f32 v[230:231], v[130:131], v[230:231], v[134:135]
	v_pk_fma_f32 v[86:87], v[212:213], s[34:35], v[86:87] op_sel_hi:[1,0,1]
	v_pk_fma_f32 v[84:85], v[184:185], s[34:35], v[84:85] op_sel_hi:[1,0,1]
	v_pk_fma_f32 v[82:83], v[230:231], s[34:35], v[82:83] op_sel_hi:[1,0,1]
	v_pk_fma_f32 v[80:81], v[218:219], s[34:35], v[80:81] op_sel_hi:[1,0,1]
	v_cvt_pk_bf16_f32 v230, v84, v85
	v_cvt_pk_bf16_f32 v231, v86, v87
	v_cvt_pk_bf16_f32 v232, v80, v81
	v_cvt_pk_bf16_f32 v233, v82, v83
	global_store_dwordx4 v[208:209], v[230:233], off
	s_nop 0
	v_pk_mul_f32 v[218:219], v[182:183], s[30:31] op_sel:[1,0] op_sel_hi:[0,0]
	v_fma_f32 v182, -v219, v219, v218
	v_max_f32_e32 v182, 0, v182
	v_add_f32_e32 v182, 0x3727c5ac, v182
	v_mul_f32_e32 v183, 0x4f800000, v182
	v_cmp_gt_f32_e32 vcc, s63, v182
	s_nop 1
	v_cndmask_b32_e32 v182, v182, v183, vcc
	v_sqrt_f32_e32 v183, v182
	s_nop 0
	v_add_u32_e32 v184, -1, v183
	v_add_u32_e32 v185, 1, v183
	v_fma_f32 v212, -v184, v183, v182
	v_fma_f32 v213, -v185, v183, v182
	v_cmp_ge_f32_e64 s[0:1], 0, v212
	s_nop 1
	v_cndmask_b32_e64 v183, v183, v184, s[0:1]
	v_cmp_lt_f32_e64 s[0:1], 0, v213
	v_lshl_add_u64 v[212:213], v[180:181], 0, v[178:179]
	global_load_dwordx4 v[238:241], v[212:213], off
	s_waitcnt vmcnt(2)
	v_and_b32_e32 v181, 0xffff0000, v247
	v_cndmask_b32_e64 v183, v183, v185, s[0:1]
	v_mul_f32_e32 v184, 0x37800000, v183
	v_cndmask_b32_e32 v183, v183, v184, vcc
	v_cmp_class_f32_e32 vcc, v182, v229
	v_and_b32_e32 v185, 0xffff0000, v249
	v_sub_f32_e32 v181, v181, v219
	v_cndmask_b32_e32 v182, v183, v182, vcc
	v_div_scale_f32 v183, s[0:1], v182, v182, 1.0
	v_rcp_f32_e32 v184, v183
	v_div_scale_f32 v178, vcc, 1.0, v182, 1.0
	v_sub_f32_e32 v185, v185, v219
	v_fma_f32 v179, -v183, v184, 1.0
	v_fmac_f32_e32 v184, v179, v184
	v_mul_f32_e32 v179, v178, v184
	v_fma_f32 v180, -v183, v179, v178
	v_fmac_f32_e32 v179, v180, v184
	v_fma_f32 v178, -v183, v179, v178
	v_div_fmas_f32 v178, v178, v184, v179
	v_div_fixup_f32 v218, v178, v182, 1.0
	v_lshlrev_b32_e32 v178, 16, v246
	v_and_b32_e32 v179, 0xffff0000, v246
	v_lshlrev_b32_e32 v180, 16, v247
	v_lshlrev_b32_e32 v182, 16, v248
	v_and_b32_e32 v183, 0xffff0000, v248
	v_lshlrev_b32_e32 v184, 16, v249
	v_sub_f32_e32 v179, v179, v219
	v_sub_f32_e32 v178, v178, v219
	v_sub_f32_e32 v180, v180, v219
	v_sub_f32_e32 v183, v183, v219
	v_sub_f32_e32 v182, v182, v219
	v_sub_f32_e32 v184, v184, v219
	v_pk_mul_f32 v[180:181], v[218:219], v[180:181] op_sel_hi:[0,1]
	v_pk_mul_f32 v[178:179], v[218:219], v[178:179] op_sel_hi:[0,1]
	v_pk_mul_f32 v[184:185], v[218:219], v[184:185] op_sel_hi:[0,1]
	v_pk_mul_f32 v[182:183], v[218:219], v[182:183] op_sel_hi:[0,1]
	v_pk_fma_f32 v[178:179], v[136:137], v[178:179], v[140:141]
	v_pk_fma_f32 v[180:181], v[138:139], v[180:181], v[142:143]
	v_pk_fma_f32 v[230:231], v[128:129], v[182:183], v[132:133]
	v_pk_fma_f32 v[232:233], v[130:131], v[184:185], v[134:135]
	v_pk_fma_f32 v[182:183], v[180:181], s[34:35], v[78:79] op_sel_hi:[1,0,1]
	v_pk_fma_f32 v[184:185], v[178:179], s[34:35], v[76:77] op_sel_hi:[1,0,1]
	v_pk_fma_f32 v[178:179], v[232:233], s[34:35], v[74:75] op_sel_hi:[1,0,1]
	v_pk_fma_f32 v[180:181], v[230:231], s[34:35], v[72:73] op_sel_hi:[1,0,1]
	v_cvt_pk_bf16_f32 v72, v184, v185
	v_cvt_pk_bf16_f32 v73, v182, v183
	v_cvt_pk_bf16_f32 v74, v180, v181
	v_cvt_pk_bf16_f32 v75, v178, v179
	global_store_dwordx4 v[214:215], v[72:75], off
	s_nop 0
	v_fma_f32 v76, -v203, v203, v202
	v_max_f32_e32 v76, 0, v76
	v_add_f32_e32 v76, 0x3727c5ac, v76
	v_mul_f32_e32 v77, 0x4f800000, v76
	v_cmp_gt_f32_e32 vcc, s63, v76
	s_waitcnt vmcnt(1)
	v_lshlrev_b32_e32 v231, 16, v241
	v_cndmask_b32_e32 v76, v76, v77, vcc
	v_sqrt_f32_e32 v77, v76
	v_and_b32_e32 v232, 0xffff0000, v241
	v_add_u32_e32 v78, -1, v77
	v_add_u32_e32 v79, 1, v77
	v_fma_f32 v202, -v78, v77, v76
	v_fma_f32 v230, -v79, v77, v76
	v_cmp_ge_f32_e64 s[0:1], 0, v202
	s_nop 1
	v_cndmask_b32_e64 v77, v77, v78, s[0:1]
	v_cmp_lt_f32_e64 s[0:1], 0, v230
	s_nop 1
	v_cndmask_b32_e64 v77, v77, v79, s[0:1]
	v_mul_f32_e32 v78, 0x37800000, v77
	v_cndmask_b32_e32 v77, v77, v78, vcc
	v_cmp_class_f32_e32 vcc, v76, v229
	s_nop 1
	v_cndmask_b32_e32 v76, v77, v76, vcc
	v_div_scale_f32 v77, s[0:1], v76, v76, 1.0
	v_rcp_f32_e32 v78, v77
	v_div_scale_f32 v79, vcc, 1.0, v76, 1.0
	v_fma_f32 v202, -v77, v78, 1.0
	v_fmac_f32_e32 v78, v202, v78
	v_mul_f32_e32 v202, v79, v78
	v_fma_f32 v230, -v77, v202, v79
	v_fmac_f32_e32 v202, v230, v78
	v_fma_f32 v77, -v77, v202, v79
	v_div_fmas_f32 v77, v77, v78, v202
	v_div_fixup_f32 v202, v77, v76, 1.0
	v_lshlrev_b32_e32 v76, 16, v238
	v_and_b32_e32 v72, 0xffff0000, v238
	v_lshlrev_b32_e32 v77, 16, v239
	v_and_b32_e32 v78, 0xffff0000, v239
	v_lshlrev_b32_e32 v79, 16, v240
	v_and_b32_e32 v230, 0xffff0000, v240
	v_sub_f32_e32 v73, v72, v203
	v_sub_f32_e32 v72, v76, v203
	v_sub_f32_e32 v75, v78, v203
	v_sub_f32_e32 v74, v77, v203
	v_sub_f32_e32 v77, v230, v203
	v_sub_f32_e32 v76, v79, v203
	v_sub_f32_e32 v79, v232, v203
	v_sub_f32_e32 v78, v231, v203
	v_pk_mul_f32 v[74:75], v[202:203], v[74:75] op_sel_hi:[0,1]
	v_pk_mul_f32 v[72:73], v[202:203], v[72:73] op_sel_hi:[0,1]
	v_pk_mul_f32 v[78:79], v[202:203], v[78:79] op_sel_hi:[0,1]
	v_pk_mul_f32 v[76:77], v[202:203], v[76:77] op_sel_hi:[0,1]
	v_pk_fma_f32 v[72:73], v[136:137], v[72:73], v[140:141]
	v_pk_fma_f32 v[74:75], v[138:139], v[74:75], v[142:143]
	v_pk_fma_f32 v[76:77], v[128:129], v[76:77], v[132:133]
	v_pk_fma_f32 v[78:79], v[130:131], v[78:79], v[134:135]
	v_pk_fma_f32 v[130:131], v[74:75], s[34:35], v[70:71] op_sel_hi:[1,0,1]
	v_pk_fma_f32 v[134:135], v[72:73], s[34:35], v[68:69] op_sel_hi:[1,0,1]
	v_pk_fma_f32 v[128:129], v[78:79], s[34:35], v[66:67] op_sel_hi:[1,0,1]
	v_pk_fma_f32 v[132:133], v[76:77], s[34:35], v[64:65] op_sel_hi:[1,0,1]
	v_cvt_pk_bf16_f32 v64, v134, v135
	v_cvt_pk_bf16_f32 v65, v130, v131
	v_cvt_pk_bf16_f32 v66, v132, v133
	v_cvt_pk_bf16_f32 v67, v128, v129
	global_store_dwordx4 v[212:213], v[64:67], off
	global_load_dwordx4 v[136:139], v[176:177], off offset:256
	global_load_dwordx4 v[68:71], v[190:191], off offset:512
	global_load_dwordx4 v[72:75], v[188:189], off offset:512
	global_load_dwordx4 v[64:67], v[188:189], off offset:528
	global_load_dwordx4 v[76:79], v[190:191], off offset:528
	s_waitcnt vmcnt(0)
	v_lshlrev_b32_e32 v140, 16, v136
	v_and_b32_e32 v136, 0xffff0000, v136
	v_lshlrev_b32_e32 v141, 16, v137
	v_and_b32_e32 v142, 0xffff0000, v137
	v_lshlrev_b32_e32 v143, 16, v138
	v_and_b32_e32 v188, 0xffff0000, v138
	v_lshlrev_b32_e32 v189, 16, v139
	v_and_b32_e32 v190, 0xffff0000, v139
	v_sub_f32_e32 v137, v136, v187
	v_sub_f32_e32 v136, v140, v187
	v_sub_f32_e32 v139, v142, v187
	v_sub_f32_e32 v138, v141, v187
	v_sub_f32_e32 v141, v188, v187
	v_sub_f32_e32 v140, v143, v187
	v_sub_f32_e32 v143, v190, v187
	v_sub_f32_e32 v142, v189, v187
	v_pk_mul_f32 v[138:139], v[186:187], v[138:139] op_sel_hi:[0,1]
	v_pk_mul_f32 v[136:137], v[186:187], v[136:137] op_sel_hi:[0,1]
	v_pk_mul_f32 v[142:143], v[186:187], v[142:143] op_sel_hi:[0,1]
	v_pk_mul_f32 v[140:141], v[186:187], v[140:141] op_sel_hi:[0,1]
	v_pk_fma_f32 v[136:137], v[72:73], v[136:137], v[68:69]
	v_pk_fma_f32 v[138:139], v[74:75], v[138:139], v[70:71]
	v_pk_fma_f32 v[140:141], v[64:65], v[140:141], v[76:77]
	v_pk_fma_f32 v[142:143], v[66:67], v[142:143], v[78:79]
	v_pk_fma_f32 v[62:63], v[138:139], s[34:35], v[62:63] op_sel_hi:[1,0,1]
	v_pk_fma_f32 v[60:61], v[136:137], s[34:35], v[60:61] op_sel_hi:[1,0,1]
	v_pk_fma_f32 v[58:59], v[142:143], s[34:35], v[58:59] op_sel_hi:[1,0,1]
	v_pk_fma_f32 v[56:57], v[140:141], s[34:35], v[56:57] op_sel_hi:[1,0,1]
	v_cvt_pk_bf16_f32 v136, v60, v61
	v_cvt_pk_bf16_f32 v137, v62, v63
	v_cvt_pk_bf16_f32 v138, v56, v57
	v_cvt_pk_bf16_f32 v139, v58, v59
	global_store_dwordx4 v[176:177], v[136:139], off offset:256
	global_load_dwordx4 v[238:241], v[192:193], off offset:256
	global_load_dwordx4 v[246:249], v[198:199], off offset:256
	global_load_dwordx4 v[242:245], v[194:195], off offset:256
	s_waitcnt vmcnt(2)
	v_lshlrev_b32_e32 v140, 16, v238
	v_and_b32_e32 v136, 0xffff0000, v238
	v_lshlrev_b32_e32 v141, 16, v239
	v_and_b32_e32 v142, 0xffff0000, v239
	v_lshlrev_b32_e32 v143, 16, v240
	v_and_b32_e32 v176, 0xffff0000, v240
	v_lshlrev_b32_e32 v177, 16, v241
	v_and_b32_e32 v186, 0xffff0000, v241
	v_sub_f32_e32 v137, v136, v197
	v_sub_f32_e32 v136, v140, v197
	v_sub_f32_e32 v139, v142, v197
	v_sub_f32_e32 v138, v141, v197
	v_sub_f32_e32 v141, v176, v197
	v_sub_f32_e32 v140, v143, v197
	v_sub_f32_e32 v143, v186, v197
	v_sub_f32_e32 v142, v177, v197
	v_pk_mul_f32 v[138:139], v[196:197], v[138:139] op_sel_hi:[0,1]
	v_pk_mul_f32 v[136:137], v[196:197], v[136:137] op_sel_hi:[0,1]
	v_pk_mul_f32 v[142:143], v[196:197], v[142:143] op_sel_hi:[0,1]
	v_pk_mul_f32 v[140:141], v[196:197], v[140:141] op_sel_hi:[0,1]
	v_pk_fma_f32 v[136:137], v[72:73], v[136:137], v[68:69]
	v_pk_fma_f32 v[138:139], v[74:75], v[138:139], v[70:71]
	v_pk_fma_f32 v[140:141], v[64:65], v[140:141], v[76:77]
	v_pk_fma_f32 v[142:143], v[66:67], v[142:143], v[78:79]
	v_pk_fma_f32 v[54:55], v[138:139], s[34:35], v[54:55] op_sel_hi:[1,0,1]
	v_pk_fma_f32 v[52:53], v[136:137], s[34:35], v[52:53] op_sel_hi:[1,0,1]
	v_pk_fma_f32 v[50:51], v[142:143], s[34:35], v[50:51] op_sel_hi:[1,0,1]
	v_pk_fma_f32 v[48:49], v[140:141], s[34:35], v[48:49] op_sel_hi:[1,0,1]
	v_cvt_pk_bf16_f32 v136, v52, v53
	v_cvt_pk_bf16_f32 v137, v54, v55
	v_cvt_pk_bf16_f32 v138, v48, v49
	v_cvt_pk_bf16_f32 v139, v50, v51
	global_store_dwordx4 v[192:193], v[136:139], off offset:256
	s_nop 0
	global_load_dwordx4 v[238:241], v[204:205], off offset:256
	s_waitcnt vmcnt(2)
	v_lshlrev_b32_e32 v140, 16, v242
	v_and_b32_e32 v136, 0xffff0000, v242
	v_lshlrev_b32_e32 v141, 16, v243
	v_and_b32_e32 v142, 0xffff0000, v243
	v_lshlrev_b32_e32 v143, 16, v244
	v_and_b32_e32 v176, 0xffff0000, v244
	v_lshlrev_b32_e32 v177, 16, v245
	v_and_b32_e32 v186, 0xffff0000, v245
	v_sub_f32_e32 v137, v136, v201
	v_sub_f32_e32 v136, v140, v201
	v_sub_f32_e32 v139, v142, v201
	v_sub_f32_e32 v138, v141, v201
	v_sub_f32_e32 v141, v176, v201
	v_sub_f32_e32 v140, v143, v201
	v_sub_f32_e32 v143, v186, v201
	v_sub_f32_e32 v142, v177, v201
	v_pk_mul_f32 v[138:139], v[200:201], v[138:139] op_sel_hi:[0,1]
	v_pk_mul_f32 v[136:137], v[200:201], v[136:137] op_sel_hi:[0,1]
	v_pk_mul_f32 v[142:143], v[200:201], v[142:143] op_sel_hi:[0,1]
	v_pk_mul_f32 v[140:141], v[200:201], v[140:141] op_sel_hi:[0,1]
	v_pk_fma_f32 v[136:137], v[72:73], v[136:137], v[68:69]
	v_pk_fma_f32 v[138:139], v[74:75], v[138:139], v[70:71]
	v_pk_fma_f32 v[140:141], v[64:65], v[140:141], v[76:77]
	v_pk_fma_f32 v[142:143], v[66:67], v[142:143], v[78:79]
	v_pk_fma_f32 v[46:47], v[138:139], s[34:35], v[46:47] op_sel_hi:[1,0,1]
	v_pk_fma_f32 v[44:45], v[136:137], s[34:35], v[44:45] op_sel_hi:[1,0,1]
	v_pk_fma_f32 v[42:43], v[142:143], s[34:35], v[42:43] op_sel_hi:[1,0,1]
	v_pk_fma_f32 v[40:41], v[140:141], s[34:35], v[40:41] op_sel_hi:[1,0,1]
	v_cvt_pk_bf16_f32 v136, v44, v45
	v_cvt_pk_bf16_f32 v137, v46, v47
	v_cvt_pk_bf16_f32 v138, v40, v41
	v_cvt_pk_bf16_f32 v139, v42, v43
	global_store_dwordx4 v[194:195], v[136:139], off offset:256
	s_nop 0
	global_load_dwordx4 v[242:245], v[208:209], off offset:256
	s_waitcnt vmcnt(5)
	v_lshlrev_b32_e32 v140, 16, v246
	v_and_b32_e32 v136, 0xffff0000, v246
	v_lshlrev_b32_e32 v141, 16, v247
	v_and_b32_e32 v142, 0xffff0000, v247
	v_lshlrev_b32_e32 v143, 16, v248
	v_and_b32_e32 v176, 0xffff0000, v248
	v_lshlrev_b32_e32 v177, 16, v249
	v_and_b32_e32 v186, 0xffff0000, v249
	v_sub_f32_e32 v137, v136, v207
	v_sub_f32_e32 v136, v140, v207
	v_sub_f32_e32 v139, v142, v207
	v_sub_f32_e32 v138, v141, v207
	v_sub_f32_e32 v141, v176, v207
	v_sub_f32_e32 v140, v143, v207
	v_sub_f32_e32 v143, v186, v207
	v_sub_f32_e32 v142, v177, v207
	v_pk_mul_f32 v[138:139], v[206:207], v[138:139] op_sel_hi:[0,1]
	v_pk_mul_f32 v[136:137], v[206:207], v[136:137] op_sel_hi:[0,1]
	v_pk_mul_f32 v[142:143], v[206:207], v[142:143] op_sel_hi:[0,1]
	v_pk_mul_f32 v[140:141], v[206:207], v[140:141] op_sel_hi:[0,1]
	v_pk_fma_f32 v[136:137], v[72:73], v[136:137], v[68:69]
	v_pk_fma_f32 v[138:139], v[74:75], v[138:139], v[70:71]
	v_pk_fma_f32 v[140:141], v[64:65], v[140:141], v[76:77]
	v_pk_fma_f32 v[142:143], v[66:67], v[142:143], v[78:79]
	v_pk_fma_f32 v[38:39], v[138:139], s[34:35], v[38:39] op_sel_hi:[1,0,1]
	v_pk_fma_f32 v[36:37], v[136:137], s[34:35], v[36:37] op_sel_hi:[1,0,1]
	v_pk_fma_f32 v[34:35], v[142:143], s[34:35], v[34:35] op_sel_hi:[1,0,1]
	v_pk_fma_f32 v[32:33], v[140:141], s[34:35], v[32:33] op_sel_hi:[1,0,1]
	v_cvt_pk_bf16_f32 v136, v36, v37
	v_cvt_pk_bf16_f32 v137, v38, v39
	v_cvt_pk_bf16_f32 v138, v32, v33
	v_cvt_pk_bf16_f32 v139, v34, v35
	global_store_dwordx4 v[198:199], v[136:139], off offset:256
	s_nop 0
	global_load_dwordx4 v[246:249], v[214:215], off offset:256
	s_waitcnt vmcnt(4)
	v_lshlrev_b32_e32 v140, 16, v238
	v_and_b32_e32 v136, 0xffff0000, v238
	v_lshlrev_b32_e32 v141, 16, v239
	v_and_b32_e32 v142, 0xffff0000, v239
	v_lshlrev_b32_e32 v143, 16, v240
	v_and_b32_e32 v176, 0xffff0000, v240
	v_lshlrev_b32_e32 v177, 16, v241
	v_and_b32_e32 v186, 0xffff0000, v241
	v_sub_f32_e32 v137, v136, v211
	v_sub_f32_e32 v136, v140, v211
	v_sub_f32_e32 v139, v142, v211
	v_sub_f32_e32 v138, v141, v211
	v_sub_f32_e32 v141, v176, v211
	v_sub_f32_e32 v140, v143, v211
	v_sub_f32_e32 v143, v186, v211
	v_sub_f32_e32 v142, v177, v211
	v_pk_mul_f32 v[138:139], v[210:211], v[138:139] op_sel_hi:[0,1]
	v_pk_mul_f32 v[136:137], v[210:211], v[136:137] op_sel_hi:[0,1]
	v_pk_mul_f32 v[142:143], v[210:211], v[142:143] op_sel_hi:[0,1]
	v_pk_mul_f32 v[140:141], v[210:211], v[140:141] op_sel_hi:[0,1]
	v_pk_fma_f32 v[136:137], v[72:73], v[136:137], v[68:69]
	v_pk_fma_f32 v[138:139], v[74:75], v[138:139], v[70:71]
	v_pk_fma_f32 v[140:141], v[64:65], v[140:141], v[76:77]
	v_pk_fma_f32 v[142:143], v[66:67], v[142:143], v[78:79]
	v_pk_fma_f32 v[30:31], v[138:139], s[34:35], v[30:31] op_sel_hi:[1,0,1]
	v_pk_fma_f32 v[28:29], v[136:137], s[34:35], v[28:29] op_sel_hi:[1,0,1]
	v_pk_fma_f32 v[26:27], v[142:143], s[34:35], v[26:27] op_sel_hi:[1,0,1]
	v_pk_fma_f32 v[24:25], v[140:141], s[34:35], v[24:25] op_sel_hi:[1,0,1]
	v_cvt_pk_bf16_f32 v136, v28, v29
	v_cvt_pk_bf16_f32 v137, v30, v31
	v_cvt_pk_bf16_f32 v138, v24, v25
	v_cvt_pk_bf16_f32 v139, v26, v27
	global_store_dwordx4 v[204:205], v[136:139], off offset:256
	s_nop 0
	global_load_dwordx4 v[238:241], v[212:213], off offset:256
	s_waitcnt vmcnt(4)
	v_lshlrev_b32_e32 v140, 16, v242
	v_and_b32_e32 v136, 0xffff0000, v242
	v_lshlrev_b32_e32 v141, 16, v243
	v_and_b32_e32 v142, 0xffff0000, v243
	v_lshlrev_b32_e32 v143, 16, v244
	v_and_b32_e32 v176, 0xffff0000, v244
	v_lshlrev_b32_e32 v177, 16, v245
	v_and_b32_e32 v186, 0xffff0000, v245
	v_sub_f32_e32 v137, v136, v217
	v_sub_f32_e32 v136, v140, v217
	v_sub_f32_e32 v139, v142, v217
	v_sub_f32_e32 v138, v141, v217
	v_sub_f32_e32 v141, v176, v217
	v_sub_f32_e32 v140, v143, v217
	v_sub_f32_e32 v143, v186, v217
	v_sub_f32_e32 v142, v177, v217
	v_pk_mul_f32 v[138:139], v[216:217], v[138:139] op_sel_hi:[0,1]
	v_pk_mul_f32 v[136:137], v[216:217], v[136:137] op_sel_hi:[0,1]
	v_pk_mul_f32 v[142:143], v[216:217], v[142:143] op_sel_hi:[0,1]
	v_pk_mul_f32 v[140:141], v[216:217], v[140:141] op_sel_hi:[0,1]
	v_pk_fma_f32 v[136:137], v[72:73], v[136:137], v[68:69]
	v_pk_fma_f32 v[138:139], v[74:75], v[138:139], v[70:71]
	v_pk_fma_f32 v[140:141], v[64:65], v[140:141], v[76:77]
	v_pk_fma_f32 v[142:143], v[66:67], v[142:143], v[78:79]
	v_pk_fma_f32 v[22:23], v[138:139], s[34:35], v[22:23] op_sel_hi:[1,0,1]
	v_pk_fma_f32 v[20:21], v[136:137], s[34:35], v[20:21] op_sel_hi:[1,0,1]
	v_pk_fma_f32 v[18:19], v[142:143], s[34:35], v[18:19] op_sel_hi:[1,0,1]
	v_pk_fma_f32 v[16:17], v[140:141], s[34:35], v[16:17] op_sel_hi:[1,0,1]
	v_cvt_pk_bf16_f32 v136, v20, v21
	v_cvt_pk_bf16_f32 v137, v22, v23
	v_cvt_pk_bf16_f32 v138, v16, v17
	v_cvt_pk_bf16_f32 v139, v18, v19
	global_store_dwordx4 v[208:209], v[136:139], off offset:256
	s_nop 0
	s_waitcnt vmcnt(3)
	v_lshlrev_b32_e32 v140, 16, v246
	v_and_b32_e32 v136, 0xffff0000, v246
	v_lshlrev_b32_e32 v141, 16, v247
	v_and_b32_e32 v142, 0xffff0000, v247
	v_lshlrev_b32_e32 v143, 16, v248
	v_and_b32_e32 v176, 0xffff0000, v248
	v_lshlrev_b32_e32 v177, 16, v249
	v_and_b32_e32 v186, 0xffff0000, v249
	v_sub_f32_e32 v137, v136, v219
	v_sub_f32_e32 v136, v140, v219
	v_sub_f32_e32 v139, v142, v219
	v_sub_f32_e32 v138, v141, v219
	v_sub_f32_e32 v141, v176, v219
	v_sub_f32_e32 v140, v143, v219
	v_sub_f32_e32 v143, v186, v219
	v_sub_f32_e32 v142, v177, v219
	v_pk_mul_f32 v[138:139], v[218:219], v[138:139] op_sel_hi:[0,1]
	v_pk_mul_f32 v[136:137], v[218:219], v[136:137] op_sel_hi:[0,1]
	v_pk_mul_f32 v[142:143], v[218:219], v[142:143] op_sel_hi:[0,1]
	v_pk_mul_f32 v[140:141], v[218:219], v[140:141] op_sel_hi:[0,1]
	v_pk_fma_f32 v[136:137], v[72:73], v[136:137], v[68:69]
	v_pk_fma_f32 v[138:139], v[74:75], v[138:139], v[70:71]
	v_pk_fma_f32 v[140:141], v[64:65], v[140:141], v[76:77]
	v_pk_fma_f32 v[142:143], v[66:67], v[142:143], v[78:79]
	v_pk_fma_f32 v[14:15], v[138:139], s[34:35], v[14:15] op_sel_hi:[1,0,1]
	v_pk_fma_f32 v[12:13], v[136:137], s[34:35], v[12:13] op_sel_hi:[1,0,1]
	v_pk_fma_f32 v[10:11], v[142:143], s[34:35], v[10:11] op_sel_hi:[1,0,1]
	v_pk_fma_f32 v[8:9], v[140:141], s[34:35], v[8:9] op_sel_hi:[1,0,1]
	v_cvt_pk_bf16_f32 v136, v12, v13
	v_cvt_pk_bf16_f32 v137, v14, v15
	v_cvt_pk_bf16_f32 v138, v8, v9
	v_cvt_pk_bf16_f32 v139, v10, v11
	global_store_dwordx4 v[214:215], v[136:139], off offset:256
	s_nop 0
	v_add_f32_e32 v140, v124, v125
	v_add_f32_e32 v141, v126, v127
	v_add_f32_e32 v142, v120, v121
	v_add_f32_e32 v143, v122, v123
	v_mul_f32_e32 v125, v125, v125
	v_mul_f32_e32 v127, v127, v127
	v_mul_f32_e32 v121, v121, v121
	v_mul_f32_e32 v123, v123, v123
	v_fmac_f32_e32 v125, v124, v124
	v_fmac_f32_e32 v127, v126, v126
	v_fmac_f32_e32 v121, v120, v120
	v_fmac_f32_e32 v123, v122, v122
	v_add_f32_e32 v122, v125, v127
	v_add_f32_e32 v121, v121, v123
	v_add_f32_e32 v121, v122, v121
	v_add_f32_e32 v122, v60, v61
	v_add_f32_e32 v123, v62, v63
	v_add_f32_e32 v124, v56, v57
	v_add_f32_e32 v125, v58, v59
	v_mul_f32_e32 v61, v61, v61
	v_mul_f32_e32 v63, v63, v63
	v_mul_f32_e32 v57, v57, v57
	v_mul_f32_e32 v59, v59, v59
	v_add_f32_e32 v140, v140, v141
	v_add_f32_e32 v141, v142, v143
	v_fmac_f32_e32 v61, v60, v60
	v_fmac_f32_e32 v63, v62, v62
	v_fmac_f32_e32 v57, v56, v56
	v_fmac_f32_e32 v59, v58, v58
	v_add_f32_e32 v120, v140, v141
	v_add_f32_e32 v122, v122, v123
	v_add_f32_e32 v123, v124, v125
	v_add_f32_e32 v58, v61, v63
	v_add_f32_e32 v57, v57, v59
	v_add_f32_e32 v120, 0, v120
	v_add_f32_e32 v56, v122, v123
	v_add_f32_e32 v57, v58, v57
	v_add_f32_e32 v56, v120, v56
	v_add_f32_e32 v59, v121, v57
	ds_bpermute_b32 v58, v222, v56
	ds_bpermute_b32 v60, v222, v59
	s_waitcnt lgkmcnt(0)
	v_add_f32_e32 v56, v56, v58
	v_add_f32_e32 v58, v59, v60
	ds_bpermute_b32 v57, v221, v56
	s_waitcnt vmcnt(2)
	v_lshlrev_b32_e32 v59, 16, v238
	v_and_b32_e32 v60, 0xffff0000, v238
	v_lshlrev_b32_e32 v62, 16, v239
	v_and_b32_e32 v63, 0xffff0000, v239
	v_lshlrev_b32_e32 v120, 16, v240
	v_and_b32_e32 v121, 0xffff0000, v240
	v_lshlrev_b32_e32 v122, 16, v241
	v_and_b32_e32 v123, 0xffff0000, v241
	v_sub_f32_e32 v61, v60, v203
	v_sub_f32_e32 v60, v59, v203
	v_sub_f32_e32 v63, v63, v203
	v_sub_f32_e32 v62, v62, v203
	v_sub_f32_e32 v121, v121, v203
	v_sub_f32_e32 v120, v120, v203
	v_sub_f32_e32 v123, v123, v203
	v_sub_f32_e32 v122, v122, v203
	v_pk_mul_f32 v[62:63], v[202:203], v[62:63] op_sel_hi:[0,1]
	v_pk_mul_f32 v[60:61], v[202:203], v[60:61] op_sel_hi:[0,1]
	v_pk_mul_f32 v[122:123], v[202:203], v[122:123] op_sel_hi:[0,1]
	v_pk_mul_f32 v[120:121], v[202:203], v[120:121] op_sel_hi:[0,1]
	v_pk_fma_f32 v[60:61], v[72:73], v[60:61], v[68:69]
	v_pk_fma_f32 v[62:63], v[74:75], v[62:63], v[70:71]
	v_pk_fma_f32 v[64:65], v[64:65], v[120:121], v[76:77]
	v_pk_fma_f32 v[66:67], v[66:67], v[122:123], v[78:79]
	v_pk_fma_f32 v[6:7], v[62:63], s[34:35], v[6:7] op_sel_hi:[1,0,1]
	v_pk_fma_f32 v[4:5], v[60:61], s[34:35], v[4:5] op_sel_hi:[1,0,1]
	v_pk_fma_f32 v[2:3], v[66:67], s[34:35], v[2:3] op_sel_hi:[1,0,1]
	v_pk_fma_f32 v[0:1], v[64:65], s[34:35], v[0:1] op_sel_hi:[1,0,1]
	v_cvt_pk_bf16_f32 v60, v4, v5
	v_cvt_pk_bf16_f32 v61, v6, v7
	v_cvt_pk_bf16_f32 v62, v0, v1
	v_cvt_pk_bf16_f32 v63, v2, v3
	ds_bpermute_b32 v59, v221, v58
	global_store_dwordx4 v[212:213], v[60:63], off offset:256
	s_and_saveexec_b64 s[0:1], s[6:7]
	s_cbranch_execz .LBB0_1297
	s_waitcnt lgkmcnt(0)
	v_add_f32_e32 v58, v58, v59
	v_add_f32_e32 v59, v56, v57
	v_lshl_add_u64 v[56:57], s[18:19], 0, v[164:165]
	global_atomic_add_f32 v[56:57], v59, off
	global_atomic_add_f32 v[56:57], v58, off offset:4

.LBB0_1475:
	v_lshl_add_u32 v128, s77, 8, v218
	v_ashrrev_i32_e32 v129, 31, v128
	v_lshlrev_b64 v[164:165], 3, v[128:129]
	v_lshl_add_u64 v[130:131], s[18:19], 0, v[164:165]
	v_lshl_or_b32 v186, s76, 8, v223
	global_load_dwordx2 v[188:189], v[130:131], off
	v_ashrrev_i32_e32 v187, 31, v186
	v_lshlrev_b64 v[130:131], 12, v[128:129]
	v_lshl_add_u64 v[130:131], s[16:17], 0, v[130:131]
	v_lshlrev_b64 v[178:179], 1, v[186:187]
	v_lshl_add_u64 v[176:177], v[130:131], 0, v[178:179]
	global_load_dwordx4 v[190:193], v[176:177], off
	v_or_b32_e32 v194, 16, v128
	v_or_b32_e32 v216, 32, v128
	v_or_b32_e32 v196, 48, v128
	v_add_u32_e32 v202, 0x80, v128
	v_add_u32_e32 v206, 0x90, v128
	v_add_u32_e32 v184, 0xa0, v128
	v_add_u32_e32 v180, 0xb0, v128
	v_lshlrev_b64 v[128:129], 2, v[186:187]
	v_lshl_add_u64 v[132:133], s[14:15], 0, v[128:129]
	v_lshl_add_u64 v[140:141], s[20:21], 0, v[128:129]
	global_load_dwordx4 v[128:131], v[132:133], off offset:16
	global_load_dwordx4 v[136:139], v[132:133], off
	s_nop 0
	global_load_dwordx4 v[132:135], v[140:141], off offset:16
	s_nop 0
	global_load_dwordx4 v[140:143], v[140:141], off
	v_ashrrev_i32_e32 v195, 31, v194
	v_ashrrev_i32_e32 v217, 31, v216
	v_ashrrev_i32_e32 v197, 31, v196
	v_ashrrev_i32_e32 v203, 31, v202
	v_ashrrev_i32_e32 v207, 31, v206
	v_ashrrev_i32_e32 v185, 31, v184
	v_ashrrev_i32_e32 v181, 31, v180
	v_lshlrev_b64 v[174:175], 3, v[194:195]
	v_lshlrev_b64 v[172:173], 3, v[216:217]
	v_lshlrev_b64 v[170:171], 3, v[196:197]
	v_lshlrev_b64 v[168:169], 3, v[202:203]
	v_lshlrev_b64 v[166:167], 3, v[206:207]
	v_lshlrev_b64 v[162:163], 3, v[184:185]
	v_lshlrev_b64 v[160:161], 3, v[180:181]
	v_lshl_add_u64 v[182:183], s[18:19], 0, v[174:175]
	v_lshl_add_u64 v[198:199], s[18:19], 0, v[172:173]
	v_lshl_add_u64 v[200:201], s[18:19], 0, v[170:171]
	v_lshl_add_u64 v[208:209], s[18:19], 0, v[168:169]
	v_lshl_add_u64 v[210:211], s[18:19], 0, v[166:167]
	v_lshl_add_u64 v[212:213], s[18:19], 0, v[162:163]
	v_lshl_add_u64 v[214:215], s[18:19], 0, v[160:161]
	global_load_dwordx2 v[228:229], v[182:183], off
	s_nop 0
	global_load_dwordx2 v[198:199], v[198:199], off
	s_nop 0
	global_load_dwordx2 v[204:205], v[200:201], off
	s_nop 0
	global_load_dwordx2 v[208:209], v[208:209], off
	s_nop 0
	global_load_dwordx2 v[210:211], v[210:211], off
	s_nop 0
	global_load_dwordx2 v[182:183], v[212:213], off
	global_load_dwordx2 v[200:201], v[214:215], off
	v_lshlrev_b64 v[196:197], 12, v[196:197]
	v_lshl_add_u64 v[196:197], s[16:17], 0, v[196:197]
	v_lshl_add_u64 v[196:197], v[196:197], 0, v[178:179]
	v_lshlrev_b64 v[202:203], 12, v[202:203]
	v_lshl_add_u64 v[202:203], s[16:17], 0, v[202:203]
	v_lshl_add_u64 v[202:203], v[202:203], 0, v[178:179]
	v_lshlrev_b64 v[206:207], 12, v[206:207]
	v_lshl_add_u64 v[206:207], s[16:17], 0, v[206:207]
	v_lshl_add_u64 v[206:207], v[206:207], 0, v[178:179]
	v_lshlrev_b64 v[184:185], 12, v[184:185]
	v_lshl_add_u64 v[184:185], s[16:17], 0, v[184:185]
	v_lshlrev_b64 v[180:181], 12, v[180:181]
	v_lshl_add_u64 v[180:181], s[16:17], 0, v[180:181]
	s_waitcnt vmcnt(0)
	v_pk_mul_f32 v[188:189], v[188:189], s[30:31] op_sel:[1,0] op_sel_hi:[0,0]
	v_fma_f32 v187, -v189, v189, v188
	v_max_f32_e32 v187, 0, v187
	v_add_f32_e32 v187, 0x3727c5ac, v187
	v_cmp_gt_f32_e32 vcc, s61, v187
	v_lshlrev_b32_e32 v188, 16, v190
	v_and_b32_e32 v190, 0xffff0000, v190
	v_lshlrev_b32_e32 v212, 16, v191
	v_and_b32_e32 v213, 0xffff0000, v191
	v_sub_f32_e32 v191, v190, v189
	v_sub_f32_e32 v190, v188, v189
	v_mul_f32_e32 v188, 0x4f800000, v187
	v_cndmask_b32_e32 v187, v187, v188, vcc
	v_sqrt_f32_e32 v188, v187
	v_lshlrev_b32_e32 v214, 16, v192
	v_and_b32_e32 v215, 0xffff0000, v192
	v_and_b32_e32 v231, 0xffff0000, v193
	v_sub_f32_e32 v192, v212, v189
	v_sub_f32_e32 v212, v214, v189
	v_add_u32_e32 v214, -1, v188
	v_lshlrev_b32_e32 v230, 16, v193
	v_sub_f32_e32 v193, v213, v189
	v_sub_f32_e32 v213, v215, v189
	v_sub_f32_e32 v215, v231, v189
	v_add_u32_e32 v231, 1, v188
	v_fma_f32 v232, -v214, v188, v187
	v_fma_f32 v233, -v231, v188, v187
	v_cmp_ge_f32_e64 s[0:1], 0, v232
	v_pk_mul_f32 v[198:199], v[198:199], s[30:31] op_sel:[1,0] op_sel_hi:[0,0]
	s_nop 0
	v_cndmask_b32_e64 v188, v188, v214, s[0:1]
	v_cmp_lt_f32_e64 s[0:1], 0, v233
	v_pk_mul_f32 v[204:205], v[204:205], s[30:31] op_sel:[1,0] op_sel_hi:[0,0]
	v_pk_mul_f32 v[208:209], v[208:209], s[30:31] op_sel:[1,0] op_sel_hi:[0,0]
	v_cndmask_b32_e64 v188, v188, v231, s[0:1]
	v_mul_f32_e32 v214, 0x37800000, v188
	v_cndmask_b32_e32 v188, v188, v214, vcc
	v_cmp_class_f32_e32 vcc, v187, v227
	v_sub_f32_e32 v214, v230, v189
	v_pk_mul_f32 v[200:201], v[200:201], s[30:31] op_sel:[1,0] op_sel_hi:[0,0]
	v_cndmask_b32_e32 v187, v188, v187, vcc
	v_div_scale_f32 v188, s[0:1], v187, v187, 1.0
	v_rcp_f32_e32 v231, v188
	v_div_scale_f32 v230, vcc, 1.0, v187, 1.0
	v_fma_f32 v232, -v188, v231, 1.0
	v_fmac_f32_e32 v231, v232, v231
	v_mul_f32_e32 v232, v230, v231
	v_fma_f32 v233, -v188, v232, v230
	v_fmac_f32_e32 v232, v233, v231
	v_fma_f32 v188, -v188, v232, v230
	v_div_fmas_f32 v188, v188, v231, v232
	v_div_fixup_f32 v188, v188, v187, 1.0
	v_pk_mul_f32 v[192:193], v[188:189], v[192:193] op_sel_hi:[0,1]
	v_pk_mul_f32 v[190:191], v[188:189], v[190:191] op_sel_hi:[0,1]
	v_pk_mul_f32 v[214:215], v[188:189], v[214:215] op_sel_hi:[0,1]
	v_pk_mul_f32 v[212:213], v[188:189], v[212:213] op_sel_hi:[0,1]
	v_pk_fma_f32 v[190:191], v[136:137], v[190:191], v[140:141]
	v_pk_fma_f32 v[192:193], v[138:139], v[192:193], v[142:143]
	v_pk_fma_f32 v[212:213], v[128:129], v[212:213], v[132:133]
	v_pk_fma_f32 v[214:215], v[130:131], v[214:215], v[134:135]
	v_pk_fma_f32 v[126:127], v[192:193], s[34:35], v[126:127] op_sel_hi:[1,0,1]
	v_pk_fma_f32 v[124:125], v[190:191], s[34:35], v[124:125] op_sel_hi:[1,0,1]
	v_pk_fma_f32 v[122:123], v[214:215], s[34:35], v[122:123] op_sel_hi:[1,0,1]
	v_pk_fma_f32 v[120:121], v[212:213], s[34:35], v[120:121] op_sel_hi:[1,0,1]
	v_cvt_pk_bf16_f32 v190, v124, v125
	v_cvt_pk_bf16_f32 v191, v126, v127
	v_cvt_pk_bf16_f32 v192, v120, v121
	v_cvt_pk_bf16_f32 v193, v122, v123
	global_store_dwordx4 v[176:177], v[190:193], off
	s_nop 1
	v_lshlrev_b64 v[190:191], 12, v[194:195]
	v_lshl_add_u64 v[190:191], s[16:17], 0, v[190:191]
	v_lshl_add_u64 v[190:191], v[190:191], 0, v[178:179]
	global_load_dwordx4 v[234:237], v[190:191], off
	v_pk_mul_f32 v[194:195], v[228:229], s[30:31] op_sel:[1,0] op_sel_hi:[0,0]
	v_fma_f32 v187, -v195, v195, v194
	v_max_f32_e32 v187, 0, v187
	v_add_f32_e32 v187, 0x3727c5ac, v187
	v_mul_f32_e32 v192, 0x4f800000, v187
	v_cmp_gt_f32_e32 vcc, s61, v187
	global_load_dwordx4 v[246:249], v[202:203], off
	global_load_dwordx4 v[242:245], v[196:197], off
	s_waitcnt vmcnt(2)
	v_lshlrev_b32_e32 v230, 16, v237
	v_cndmask_b32_e32 v187, v187, v192, vcc
	v_sqrt_f32_e32 v194, v187
	v_lshlrev_b64 v[192:193], 12, v[216:217]
	v_and_b32_e32 v231, 0xffff0000, v237
	v_lshl_add_u64 v[192:193], s[16:17], 0, v[192:193]
	v_add_u32_e32 v216, -1, v194
	v_add_u32_e32 v217, 1, v194
	v_fma_f32 v228, -v216, v194, v187
	v_fma_f32 v229, -v217, v194, v187
	v_cmp_ge_f32_e64 s[0:1], 0, v228
	v_lshl_add_u64 v[192:193], v[192:193], 0, v[178:179]
	global_load_dwordx4 v[238:241], v[192:193], off
	s_nop 0
	v_cndmask_b32_e64 v194, v194, v216, s[0:1]
	v_cmp_lt_f32_e64 s[0:1], 0, v229
	s_nop 1
	v_cndmask_b32_e64 v194, v194, v217, s[0:1]
	v_mul_f32_e32 v216, 0x37800000, v194
	v_cndmask_b32_e32 v194, v194, v216, vcc
	v_cmp_class_f32_e32 vcc, v187, v227
	s_nop 1
	v_cndmask_b32_e32 v187, v194, v187, vcc
	v_div_scale_f32 v194, s[0:1], v187, v187, 1.0
	v_rcp_f32_e32 v216, v194
	v_div_scale_f32 v217, vcc, 1.0, v187, 1.0
	v_fma_f32 v228, -v194, v216, 1.0
	v_fmac_f32_e32 v216, v228, v216
	v_mul_f32_e32 v228, v217, v216
	v_fma_f32 v229, -v194, v228, v217
	v_fmac_f32_e32 v228, v229, v216
	v_fma_f32 v194, -v194, v228, v217
	v_div_fmas_f32 v194, v194, v216, v228
	v_div_fixup_f32 v194, v194, v187, 1.0
	v_lshlrev_b32_e32 v187, 16, v234
	v_and_b32_e32 v212, 0xffff0000, v234
	v_lshlrev_b32_e32 v216, 16, v235
	v_and_b32_e32 v217, 0xffff0000, v235
	v_lshlrev_b32_e32 v228, 16, v236
	v_and_b32_e32 v229, 0xffff0000, v236
	v_sub_f32_e32 v213, v212, v195
	v_sub_f32_e32 v212, v187, v195
	v_sub_f32_e32 v215, v217, v195
	v_sub_f32_e32 v214, v216, v195
	v_sub_f32_e32 v217, v229, v195
	v_sub_f32_e32 v216, v228, v195
	v_sub_f32_e32 v229, v231, v195
	v_sub_f32_e32 v228, v230, v195
	v_pk_mul_f32 v[214:215], v[194:195], v[214:215] op_sel_hi:[0,1]
	v_pk_mul_f32 v[212:213], v[194:195], v[212:213] op_sel_hi:[0,1]
	v_pk_mul_f32 v[228:229], v[194:195], v[228:229] op_sel_hi:[0,1]
	v_pk_mul_f32 v[216:217], v[194:195], v[216:217] op_sel_hi:[0,1]
	v_pk_fma_f32 v[212:213], v[136:137], v[212:213], v[140:141]
	v_pk_fma_f32 v[214:215], v[138:139], v[214:215], v[142:143]
	v_pk_fma_f32 v[216:217], v[128:129], v[216:217], v[132:133]
	v_pk_fma_f32 v[228:229], v[130:131], v[228:229], v[134:135]
	v_pk_fma_f32 v[118:119], v[214:215], s[34:35], v[118:119] op_sel_hi:[1,0,1]
	v_pk_fma_f32 v[116:117], v[212:213], s[34:35], v[116:117] op_sel_hi:[1,0,1]
	v_pk_fma_f32 v[114:115], v[228:229], s[34:35], v[114:115] op_sel_hi:[1,0,1]
	v_pk_fma_f32 v[112:113], v[216:217], s[34:35], v[112:113] op_sel_hi:[1,0,1]
	v_cvt_pk_bf16_f32 v212, v116, v117
	v_cvt_pk_bf16_f32 v213, v118, v119
	v_cvt_pk_bf16_f32 v214, v112, v113
	v_cvt_pk_bf16_f32 v215, v114, v115
	global_store_dwordx4 v[190:191], v[212:215], off
	s_nop 0
	v_fma_f32 v187, -v199, v199, v198
	v_max_f32_e32 v187, 0, v187
	v_add_f32_e32 v187, 0x3727c5ac, v187
	v_mul_f32_e32 v198, 0x4f800000, v187
	v_cmp_gt_f32_e32 vcc, s61, v187
	global_load_dwordx4 v[234:237], v[206:207], off
	s_waitcnt vmcnt(2)
	v_lshlrev_b32_e32 v230, 16, v241
	v_cndmask_b32_e32 v187, v187, v198, vcc
	v_sqrt_f32_e32 v198, v187
	v_and_b32_e32 v231, 0xffff0000, v241
	v_add_u32_e32 v216, -1, v198
	v_add_u32_e32 v217, 1, v198
	v_fma_f32 v228, -v216, v198, v187
	v_fma_f32 v229, -v217, v198, v187
	v_cmp_ge_f32_e64 s[0:1], 0, v228
	s_nop 1
	v_cndmask_b32_e64 v198, v198, v216, s[0:1]
	v_cmp_lt_f32_e64 s[0:1], 0, v229
	s_nop 1
	v_cndmask_b32_e64 v198, v198, v217, s[0:1]
	v_mul_f32_e32 v216, 0x37800000, v198
	v_cndmask_b32_e32 v198, v198, v216, vcc
	v_cmp_class_f32_e32 vcc, v187, v227
	s_nop 1
	v_cndmask_b32_e32 v187, v198, v187, vcc
	v_div_scale_f32 v198, s[0:1], v187, v187, 1.0
	v_rcp_f32_e32 v216, v198
	v_div_scale_f32 v217, vcc, 1.0, v187, 1.0
	v_fma_f32 v228, -v198, v216, 1.0
	v_fmac_f32_e32 v216, v228, v216
	v_mul_f32_e32 v228, v217, v216
	v_fma_f32 v229, -v198, v228, v217
	v_fmac_f32_e32 v228, v229, v216
	v_fma_f32 v198, -v198, v228, v217
	v_div_fmas_f32 v198, v198, v216, v228
	v_div_fixup_f32 v198, v198, v187, 1.0
	v_lshlrev_b32_e32 v187, 16, v238
	v_and_b32_e32 v212, 0xffff0000, v238
	v_lshlrev_b32_e32 v216, 16, v239
	v_and_b32_e32 v217, 0xffff0000, v239
	v_lshlrev_b32_e32 v228, 16, v240
	v_and_b32_e32 v229, 0xffff0000, v240
	v_sub_f32_e32 v213, v212, v199
	v_sub_f32_e32 v212, v187, v199
	v_sub_f32_e32 v215, v217, v199
	v_sub_f32_e32 v214, v216, v199
	v_sub_f32_e32 v217, v229, v199
	v_sub_f32_e32 v216, v228, v199
	v_sub_f32_e32 v229, v231, v199
	v_sub_f32_e32 v228, v230, v199
	v_pk_mul_f32 v[214:215], v[198:199], v[214:215] op_sel_hi:[0,1]
	v_pk_mul_f32 v[212:213], v[198:199], v[212:213] op_sel_hi:[0,1]
	v_pk_mul_f32 v[228:229], v[198:199], v[228:229] op_sel_hi:[0,1]
	v_pk_mul_f32 v[216:217], v[198:199], v[216:217] op_sel_hi:[0,1]
	v_pk_fma_f32 v[212:213], v[136:137], v[212:213], v[140:141]
	v_pk_fma_f32 v[214:215], v[138:139], v[214:215], v[142:143]
	v_pk_fma_f32 v[216:217], v[128:129], v[216:217], v[132:133]
	v_pk_fma_f32 v[228:229], v[130:131], v[228:229], v[134:135]
	v_pk_fma_f32 v[110:111], v[214:215], s[34:35], v[110:111] op_sel_hi:[1,0,1]
	v_pk_fma_f32 v[108:109], v[212:213], s[34:35], v[108:109] op_sel_hi:[1,0,1]
	v_pk_fma_f32 v[106:107], v[228:229], s[34:35], v[106:107] op_sel_hi:[1,0,1]
	v_pk_fma_f32 v[104:105], v[216:217], s[34:35], v[104:105] op_sel_hi:[1,0,1]
	v_cvt_pk_bf16_f32 v212, v108, v109
	v_cvt_pk_bf16_f32 v213, v110, v111
	v_cvt_pk_bf16_f32 v214, v104, v105
	v_cvt_pk_bf16_f32 v215, v106, v107
	global_store_dwordx4 v[192:193], v[212:215], off
	s_nop 0
	v_fma_f32 v187, -v205, v205, v204
	v_max_f32_e32 v187, 0, v187
	v_add_f32_e32 v187, 0x3727c5ac, v187
	v_mul_f32_e32 v204, 0x4f800000, v187
	v_cmp_gt_f32_e32 vcc, s61, v187
	s_waitcnt vmcnt(4)
	v_lshlrev_b32_e32 v230, 16, v245
	v_cndmask_b32_e32 v187, v187, v204, vcc
	v_sqrt_f32_e32 v204, v187
	v_and_b32_e32 v231, 0xffff0000, v245
	v_add_u32_e32 v216, -1, v204
	v_add_u32_e32 v217, 1, v204
	v_fma_f32 v228, -v216, v204, v187
	v_fma_f32 v229, -v217, v204, v187
	v_cmp_ge_f32_e64 s[0:1], 0, v228
	s_nop 1
	v_cndmask_b32_e64 v204, v204, v216, s[0:1]
	v_cmp_lt_f32_e64 s[0:1], 0, v229
	s_nop 1
	v_cndmask_b32_e64 v204, v204, v217, s[0:1]
	v_mul_f32_e32 v216, 0x37800000, v204
	v_cndmask_b32_e32 v204, v204, v216, vcc
	v_cmp_class_f32_e32 vcc, v187, v227
	s_nop 1
	v_cndmask_b32_e32 v187, v204, v187, vcc
	v_div_scale_f32 v204, s[0:1], v187, v187, 1.0
	v_rcp_f32_e32 v216, v204
	v_div_scale_f32 v217, vcc, 1.0, v187, 1.0
	v_fma_f32 v228, -v204, v216, 1.0
	v_fmac_f32_e32 v216, v228, v216
	v_mul_f32_e32 v228, v217, v216
	v_fma_f32 v229, -v204, v228, v217
	v_fmac_f32_e32 v228, v229, v216
	v_fma_f32 v204, -v204, v228, v217
	v_div_fmas_f32 v204, v204, v216, v228
	v_div_fixup_f32 v204, v204, v187, 1.0
	v_lshlrev_b32_e32 v187, 16, v242
	v_and_b32_e32 v212, 0xffff0000, v242
	v_lshlrev_b32_e32 v216, 16, v243
	v_and_b32_e32 v217, 0xffff0000, v243
	v_lshlrev_b32_e32 v228, 16, v244
	v_and_b32_e32 v229, 0xffff0000, v244
	v_sub_f32_e32 v213, v212, v205
	v_sub_f32_e32 v212, v187, v205
	v_sub_f32_e32 v215, v217, v205
	v_sub_f32_e32 v214, v216, v205
	v_sub_f32_e32 v217, v229, v205
	v_sub_f32_e32 v216, v228, v205
	v_sub_f32_e32 v229, v231, v205
	v_sub_f32_e32 v228, v230, v205
	v_pk_mul_f32 v[214:215], v[204:205], v[214:215] op_sel_hi:[0,1]
	v_pk_mul_f32 v[212:213], v[204:205], v[212:213] op_sel_hi:[0,1]
	v_pk_mul_f32 v[228:229], v[204:205], v[228:229] op_sel_hi:[0,1]
	v_pk_mul_f32 v[216:217], v[204:205], v[216:217] op_sel_hi:[0,1]
	v_pk_fma_f32 v[212:213], v[136:137], v[212:213], v[140:141]
	v_pk_fma_f32 v[214:215], v[138:139], v[214:215], v[142:143]
	v_pk_fma_f32 v[216:217], v[128:129], v[216:217], v[132:133]
	v_pk_fma_f32 v[228:229], v[130:131], v[228:229], v[134:135]
	v_pk_fma_f32 v[102:103], v[214:215], s[34:35], v[102:103] op_sel_hi:[1,0,1]
	v_pk_fma_f32 v[100:101], v[212:213], s[34:35], v[100:101] op_sel_hi:[1,0,1]
	v_pk_fma_f32 v[98:99], v[228:229], s[34:35], v[98:99] op_sel_hi:[1,0,1]
	v_pk_fma_f32 v[96:97], v[216:217], s[34:35], v[96:97] op_sel_hi:[1,0,1]
	v_cvt_pk_bf16_f32 v212, v100, v101
	v_cvt_pk_bf16_f32 v213, v102, v103
	v_cvt_pk_bf16_f32 v214, v96, v97
	v_cvt_pk_bf16_f32 v215, v98, v99
	global_store_dwordx4 v[196:197], v[212:215], off
	s_nop 0
	v_fma_f32 v187, -v209, v209, v208
	v_max_f32_e32 v187, 0, v187
	v_add_f32_e32 v187, 0x3727c5ac, v187
	v_mul_f32_e32 v208, 0x4f800000, v187
	v_cmp_gt_f32_e32 vcc, s61, v187
	s_waitcnt vmcnt(6)
	v_lshlrev_b32_e32 v230, 16, v249
	v_cndmask_b32_e32 v187, v187, v208, vcc
	v_sqrt_f32_e32 v208, v187
	v_and_b32_e32 v231, 0xffff0000, v249
	v_add_u32_e32 v216, -1, v208
	v_add_u32_e32 v217, 1, v208
	v_fma_f32 v228, -v216, v208, v187
	v_fma_f32 v229, -v217, v208, v187
	v_cmp_ge_f32_e64 s[0:1], 0, v228
	s_nop 1
	v_cndmask_b32_e64 v208, v208, v216, s[0:1]
	v_cmp_lt_f32_e64 s[0:1], 0, v229
	s_nop 1
	v_cndmask_b32_e64 v208, v208, v217, s[0:1]
	v_mul_f32_e32 v216, 0x37800000, v208
	v_cndmask_b32_e32 v208, v208, v216, vcc
	v_cmp_class_f32_e32 vcc, v187, v227
	s_nop 1
	v_cndmask_b32_e32 v187, v208, v187, vcc
	v_div_scale_f32 v208, s[0:1], v187, v187, 1.0
	v_rcp_f32_e32 v216, v208
	v_div_scale_f32 v217, vcc, 1.0, v187, 1.0
	v_fma_f32 v228, -v208, v216, 1.0
	v_fmac_f32_e32 v216, v228, v216
	v_mul_f32_e32 v228, v217, v216
	v_fma_f32 v229, -v208, v228, v217
	v_fmac_f32_e32 v228, v229, v216
	v_fma_f32 v208, -v208, v228, v217
	v_div_fmas_f32 v208, v208, v216, v228
	v_div_fixup_f32 v208, v208, v187, 1.0
	v_lshlrev_b32_e32 v187, 16, v246
	v_and_b32_e32 v212, 0xffff0000, v246
	v_lshlrev_b32_e32 v216, 16, v247
	v_and_b32_e32 v217, 0xffff0000, v247
	v_lshlrev_b32_e32 v228, 16, v248
	v_and_b32_e32 v229, 0xffff0000, v248
	v_sub_f32_e32 v213, v212, v209
	v_sub_f32_e32 v212, v187, v209
	v_sub_f32_e32 v215, v217, v209
	v_sub_f32_e32 v214, v216, v209
	v_sub_f32_e32 v217, v229, v209
	v_sub_f32_e32 v216, v228, v209
	v_sub_f32_e32 v229, v231, v209
	v_sub_f32_e32 v228, v230, v209
	v_pk_mul_f32 v[214:215], v[208:209], v[214:215] op_sel_hi:[0,1]
	v_pk_mul_f32 v[212:213], v[208:209], v[212:213] op_sel_hi:[0,1]
	v_pk_mul_f32 v[228:229], v[208:209], v[228:229] op_sel_hi:[0,1]
	v_pk_mul_f32 v[216:217], v[208:209], v[216:217] op_sel_hi:[0,1]
	v_pk_fma_f32 v[212:213], v[136:137], v[212:213], v[140:141]
	v_pk_fma_f32 v[214:215], v[138:139], v[214:215], v[142:143]
	v_pk_fma_f32 v[216:217], v[128:129], v[216:217], v[132:133]
	v_pk_fma_f32 v[228:229], v[130:131], v[228:229], v[134:135]
	v_pk_fma_f32 v[94:95], v[214:215], s[34:35], v[94:95] op_sel_hi:[1,0,1]
	v_pk_fma_f32 v[92:93], v[212:213], s[34:35], v[92:93] op_sel_hi:[1,0,1]
	v_pk_fma_f32 v[90:91], v[228:229], s[34:35], v[90:91] op_sel_hi:[1,0,1]
	v_pk_fma_f32 v[88:89], v[216:217], s[34:35], v[88:89] op_sel_hi:[1,0,1]
	v_cvt_pk_bf16_f32 v212, v92, v93
	v_cvt_pk_bf16_f32 v213, v94, v95
	v_cvt_pk_bf16_f32 v214, v88, v89
	v_cvt_pk_bf16_f32 v215, v90, v91
	global_store_dwordx4 v[202:203], v[212:215], off
	s_nop 0
	s_waitcnt vmcnt(3)
	v_lshlrev_b32_e32 v216, 16, v236
	v_pk_mul_f32 v[214:215], v[210:211], s[30:31] op_sel:[1,0] op_sel_hi:[0,0]
	v_fma_f32 v187, -v215, v215, v214
	v_max_f32_e32 v187, 0, v187
	v_add_f32_e32 v187, 0x3727c5ac, v187
	v_mul_f32_e32 v210, 0x4f800000, v187
	v_cmp_gt_f32_e32 vcc, s61, v187
	v_and_b32_e32 v217, 0xffff0000, v236
	v_sub_f32_e32 v217, v217, v215
	v_cndmask_b32_e32 v187, v187, v210, vcc
	v_sqrt_f32_e32 v210, v187
	v_sub_f32_e32 v216, v216, v215
	v_add_u32_e32 v211, -1, v210
	v_add_u32_e32 v212, 1, v210
	v_fma_f32 v213, -v211, v210, v187
	v_fma_f32 v214, -v212, v210, v187
	v_cmp_ge_f32_e64 s[0:1], 0, v213
	s_nop 1
	v_cndmask_b32_e64 v210, v210, v211, s[0:1]
	v_cmp_lt_f32_e64 s[0:1], 0, v214
	s_nop 1
	v_cndmask_b32_e64 v210, v210, v212, s[0:1]
	v_mul_f32_e32 v211, 0x37800000, v210
	v_cndmask_b32_e32 v210, v210, v211, vcc
	v_cmp_class_f32_e32 vcc, v187, v227
	v_lshl_add_u64 v[212:213], v[184:185], 0, v[178:179]
	global_load_dwordx4 v[238:241], v[212:213], off
	s_nop 0
	v_cndmask_b32_e32 v187, v210, v187, vcc
	v_div_scale_f32 v210, s[0:1], v187, v187, 1.0
	v_rcp_f32_e32 v211, v210
	v_div_scale_f32 v184, vcc, 1.0, v187, 1.0
	v_fma_f32 v185, -v210, v211, 1.0
	v_fmac_f32_e32 v211, v185, v211
	v_mul_f32_e32 v185, v184, v211
	v_fma_f32 v214, -v210, v185, v184
	v_fmac_f32_e32 v185, v214, v211
	v_fma_f32 v184, -v210, v185, v184
	v_div_fmas_f32 v184, v184, v211, v185
	v_div_fixup_f32 v214, v184, v187, 1.0
	v_lshlrev_b32_e32 v184, 16, v234
	v_and_b32_e32 v185, 0xffff0000, v234
	v_lshlrev_b32_e32 v187, 16, v235
	v_and_b32_e32 v210, 0xffff0000, v235
	v_lshlrev_b32_e32 v228, 16, v237
	v_and_b32_e32 v229, 0xffff0000, v237
	v_sub_f32_e32 v185, v185, v215
	v_sub_f32_e32 v184, v184, v215
	v_sub_f32_e32 v211, v210, v215
	v_sub_f32_e32 v210, v187, v215
	v_sub_f32_e32 v229, v229, v215
	v_sub_f32_e32 v228, v228, v215
	v_pk_mul_f32 v[210:211], v[214:215], v[210:211] op_sel_hi:[0,1]
	v_pk_mul_f32 v[184:185], v[214:215], v[184:185] op_sel_hi:[0,1]
	v_pk_mul_f32 v[228:229], v[214:215], v[228:229] op_sel_hi:[0,1]
	v_pk_mul_f32 v[216:217], v[214:215], v[216:217] op_sel_hi:[0,1]
	v_pk_fma_f32 v[184:185], v[136:137], v[184:185], v[140:141]
	v_pk_fma_f32 v[210:211], v[138:139], v[210:211], v[142:143]
	v_pk_fma_f32 v[216:217], v[128:129], v[216:217], v[132:133]
	v_pk_fma_f32 v[228:229], v[130:131], v[228:229], v[134:135]
	v_pk_fma_f32 v[86:87], v[210:211], s[34:35], v[86:87] op_sel_hi:[1,0,1]
	v_pk_fma_f32 v[84:85], v[184:185], s[34:35], v[84:85] op_sel_hi:[1,0,1]
	v_pk_fma_f32 v[82:83], v[228:229], s[34:35], v[82:83] op_sel_hi:[1,0,1]
	v_pk_fma_f32 v[80:81], v[216:217], s[34:35], v[80:81] op_sel_hi:[1,0,1]
	v_cvt_pk_bf16_f32 v228, v84, v85
	v_cvt_pk_bf16_f32 v229, v86, v87
	v_cvt_pk_bf16_f32 v230, v80, v81
	v_cvt_pk_bf16_f32 v231, v82, v83
	global_store_dwordx4 v[206:207], v[228:231], off
	s_nop 0
	v_pk_mul_f32 v[216:217], v[182:183], s[30:31] op_sel:[1,0] op_sel_hi:[0,0]
	v_fma_f32 v182, -v217, v217, v216
	v_max_f32_e32 v182, 0, v182
	v_add_f32_e32 v182, 0x3727c5ac, v182
	v_mul_f32_e32 v183, 0x4f800000, v182
	v_cmp_gt_f32_e32 vcc, s61, v182
	s_nop 1
	v_cndmask_b32_e32 v182, v182, v183, vcc
	v_sqrt_f32_e32 v183, v182
	s_nop 0
	v_add_u32_e32 v184, -1, v183
	v_add_u32_e32 v185, 1, v183
	v_fma_f32 v187, -v184, v183, v182
	v_fma_f32 v210, -v185, v183, v182
	v_cmp_ge_f32_e64 s[0:1], 0, v187
	s_nop 1
	v_cndmask_b32_e64 v183, v183, v184, s[0:1]
	v_cmp_lt_f32_e64 s[0:1], 0, v210
	v_lshl_add_u64 v[210:211], v[180:181], 0, v[178:179]
	global_load_dwordx4 v[242:245], v[210:211], off
	s_waitcnt vmcnt(2)
	v_and_b32_e32 v181, 0xffff0000, v239
	v_cndmask_b32_e64 v183, v183, v185, s[0:1]
	v_mul_f32_e32 v184, 0x37800000, v183
	v_cndmask_b32_e32 v183, v183, v184, vcc
	v_cmp_class_f32_e32 vcc, v182, v227
	v_and_b32_e32 v185, 0xffff0000, v241
	v_sub_f32_e32 v181, v181, v217
	v_cndmask_b32_e32 v182, v183, v182, vcc
	v_div_scale_f32 v183, s[0:1], v182, v182, 1.0
	v_rcp_f32_e32 v184, v183
	v_div_scale_f32 v178, vcc, 1.0, v182, 1.0
	v_sub_f32_e32 v185, v185, v217
	v_fma_f32 v179, -v183, v184, 1.0
	v_fmac_f32_e32 v184, v179, v184
	v_mul_f32_e32 v179, v178, v184
	v_fma_f32 v180, -v183, v179, v178
	v_fmac_f32_e32 v179, v180, v184
	v_fma_f32 v178, -v183, v179, v178
	v_div_fmas_f32 v178, v178, v184, v179
	v_div_fixup_f32 v216, v178, v182, 1.0
	v_lshlrev_b32_e32 v178, 16, v238
	v_and_b32_e32 v179, 0xffff0000, v238
	v_lshlrev_b32_e32 v180, 16, v239
	v_lshlrev_b32_e32 v182, 16, v240
	v_and_b32_e32 v183, 0xffff0000, v240
	v_lshlrev_b32_e32 v184, 16, v241
	v_sub_f32_e32 v179, v179, v217
	v_sub_f32_e32 v178, v178, v217
	v_sub_f32_e32 v180, v180, v217
	v_sub_f32_e32 v183, v183, v217
	v_sub_f32_e32 v182, v182, v217
	v_sub_f32_e32 v184, v184, v217
	v_pk_mul_f32 v[180:181], v[216:217], v[180:181] op_sel_hi:[0,1]
	v_pk_mul_f32 v[178:179], v[216:217], v[178:179] op_sel_hi:[0,1]
	v_pk_mul_f32 v[184:185], v[216:217], v[184:185] op_sel_hi:[0,1]
	v_pk_mul_f32 v[182:183], v[216:217], v[182:183] op_sel_hi:[0,1]
	v_pk_fma_f32 v[178:179], v[136:137], v[178:179], v[140:141]
	v_pk_fma_f32 v[180:181], v[138:139], v[180:181], v[142:143]
	v_pk_fma_f32 v[228:229], v[128:129], v[182:183], v[132:133]
	v_pk_fma_f32 v[230:231], v[130:131], v[184:185], v[134:135]
	v_pk_fma_f32 v[182:183], v[180:181], s[34:35], v[78:79] op_sel_hi:[1,0,1]
	v_pk_fma_f32 v[184:185], v[178:179], s[34:35], v[76:77] op_sel_hi:[1,0,1]
	v_pk_fma_f32 v[178:179], v[230:231], s[34:35], v[74:75] op_sel_hi:[1,0,1]
	v_pk_fma_f32 v[180:181], v[228:229], s[34:35], v[72:73] op_sel_hi:[1,0,1]
	v_cvt_pk_bf16_f32 v72, v184, v185
	v_cvt_pk_bf16_f32 v73, v182, v183
	v_cvt_pk_bf16_f32 v74, v180, v181
	v_cvt_pk_bf16_f32 v75, v178, v179
	global_store_dwordx4 v[212:213], v[72:75], off
	s_nop 0
	v_fma_f32 v76, -v201, v201, v200
	v_max_f32_e32 v76, 0, v76
	v_add_f32_e32 v76, 0x3727c5ac, v76
	v_mul_f32_e32 v77, 0x4f800000, v76
	v_cmp_gt_f32_e32 vcc, s61, v76
	s_waitcnt vmcnt(1)
	v_lshlrev_b32_e32 v228, 16, v245
	v_cndmask_b32_e32 v76, v76, v77, vcc
	v_sqrt_f32_e32 v77, v76
	v_and_b32_e32 v229, 0xffff0000, v245
	v_add_u32_e32 v78, -1, v77
	v_add_u32_e32 v79, 1, v77
	v_fma_f32 v187, -v78, v77, v76
	v_fma_f32 v200, -v79, v77, v76
	v_cmp_ge_f32_e64 s[0:1], 0, v187
	s_nop 1
	v_cndmask_b32_e64 v77, v77, v78, s[0:1]
	v_cmp_lt_f32_e64 s[0:1], 0, v200
	s_nop 1
	v_cndmask_b32_e64 v77, v77, v79, s[0:1]
	v_mul_f32_e32 v78, 0x37800000, v77
	v_cndmask_b32_e32 v77, v77, v78, vcc
	v_cmp_class_f32_e32 vcc, v76, v227
	s_nop 1
	v_cndmask_b32_e32 v76, v77, v76, vcc
	v_div_scale_f32 v77, s[0:1], v76, v76, 1.0
	v_rcp_f32_e32 v78, v77
	v_div_scale_f32 v79, vcc, 1.0, v76, 1.0
	v_fma_f32 v187, -v77, v78, 1.0
	v_fmac_f32_e32 v78, v187, v78
	v_mul_f32_e32 v187, v79, v78
	v_fma_f32 v200, -v77, v187, v79
	v_fmac_f32_e32 v187, v200, v78
	v_fma_f32 v77, -v77, v187, v79
	v_div_fmas_f32 v77, v77, v78, v187
	v_div_fixup_f32 v200, v77, v76, 1.0
	v_lshlrev_b32_e32 v76, 16, v242
	v_and_b32_e32 v72, 0xffff0000, v242
	v_lshlrev_b32_e32 v77, 16, v243
	v_and_b32_e32 v78, 0xffff0000, v243
	v_lshlrev_b32_e32 v79, 16, v244
	v_and_b32_e32 v187, 0xffff0000, v244
	v_sub_f32_e32 v73, v72, v201
	v_sub_f32_e32 v72, v76, v201
	v_sub_f32_e32 v75, v78, v201
	v_sub_f32_e32 v74, v77, v201
	v_sub_f32_e32 v77, v187, v201
	v_sub_f32_e32 v76, v79, v201
	v_sub_f32_e32 v79, v229, v201
	v_sub_f32_e32 v78, v228, v201
	v_pk_mul_f32 v[74:75], v[200:201], v[74:75] op_sel_hi:[0,1]
	v_pk_mul_f32 v[72:73], v[200:201], v[72:73] op_sel_hi:[0,1]
	v_pk_mul_f32 v[78:79], v[200:201], v[78:79] op_sel_hi:[0,1]
	v_pk_mul_f32 v[76:77], v[200:201], v[76:77] op_sel_hi:[0,1]
	v_pk_fma_f32 v[72:73], v[136:137], v[72:73], v[140:141]
	v_pk_fma_f32 v[74:75], v[138:139], v[74:75], v[142:143]
	v_pk_fma_f32 v[76:77], v[128:129], v[76:77], v[132:133]
	v_pk_fma_f32 v[78:79], v[130:131], v[78:79], v[134:135]
	v_pk_fma_f32 v[130:131], v[74:75], s[34:35], v[70:71] op_sel_hi:[1,0,1]
	v_pk_fma_f32 v[134:135], v[72:73], s[34:35], v[68:69] op_sel_hi:[1,0,1]
	v_pk_fma_f32 v[128:129], v[78:79], s[34:35], v[66:67] op_sel_hi:[1,0,1]
	v_pk_fma_f32 v[132:133], v[76:77], s[34:35], v[64:65] op_sel_hi:[1,0,1]
	v_cvt_pk_bf16_f32 v64, v134, v135
	v_cvt_pk_bf16_f32 v65, v130, v131
	v_cvt_pk_bf16_f32 v66, v132, v133
	v_cvt_pk_bf16_f32 v67, v128, v129
	global_store_dwordx4 v[210:211], v[64:67], off
	global_load_dwordx4 v[136:139], v[176:177], off offset:256
	s_waitcnt vmcnt(0)
	v_lshlrev_b32_e32 v140, 16, v136
	v_or_b32_e32 v64, 0x80, v186
	v_ashrrev_i32_e32 v65, 31, v64
	v_lshlrev_b64 v[64:65], 2, v[64:65]
	v_lshl_add_u64 v[66:67], s[14:15], 0, v[64:65]
	v_lshl_add_u64 v[76:77], s[20:21], 0, v[64:65]
	global_load_dwordx4 v[68:71], v[76:77], off
	global_load_dwordx4 v[72:75], v[66:67], off
	s_nop 0
	global_load_dwordx4 v[64:67], v[66:67], off offset:16
	s_nop 0
	global_load_dwordx4 v[76:79], v[76:77], off offset:16
	v_and_b32_e32 v136, 0xffff0000, v136
	v_lshlrev_b32_e32 v141, 16, v137
	v_and_b32_e32 v142, 0xffff0000, v137
	v_lshlrev_b32_e32 v143, 16, v138
	v_and_b32_e32 v186, 0xffff0000, v138
	v_lshlrev_b32_e32 v187, 16, v139
	v_and_b32_e32 v228, 0xffff0000, v139
	v_sub_f32_e32 v137, v136, v189
	v_sub_f32_e32 v136, v140, v189
	v_sub_f32_e32 v139, v142, v189
	v_sub_f32_e32 v138, v141, v189
	v_sub_f32_e32 v141, v186, v189
	v_sub_f32_e32 v140, v143, v189
	v_sub_f32_e32 v143, v228, v189
	v_sub_f32_e32 v142, v187, v189
	v_pk_mul_f32 v[138:139], v[188:189], v[138:139] op_sel_hi:[0,1]
	v_pk_mul_f32 v[136:137], v[188:189], v[136:137] op_sel_hi:[0,1]
	v_pk_mul_f32 v[142:143], v[188:189], v[142:143] op_sel_hi:[0,1]
	v_pk_mul_f32 v[140:141], v[188:189], v[140:141] op_sel_hi:[0,1]
	s_waitcnt vmcnt(0)
	v_pk_fma_f32 v[136:137], v[72:73], v[136:137], v[68:69]
	v_pk_fma_f32 v[138:139], v[74:75], v[138:139], v[70:71]
	v_pk_fma_f32 v[140:141], v[64:65], v[140:141], v[76:77]
	v_pk_fma_f32 v[142:143], v[66:67], v[142:143], v[78:79]
	v_pk_fma_f32 v[62:63], v[138:139], s[34:35], v[62:63] op_sel_hi:[1,0,1]
	v_pk_fma_f32 v[60:61], v[136:137], s[34:35], v[60:61] op_sel_hi:[1,0,1]
	v_pk_fma_f32 v[58:59], v[142:143], s[34:35], v[58:59] op_sel_hi:[1,0,1]
	v_pk_fma_f32 v[56:57], v[140:141], s[34:35], v[56:57] op_sel_hi:[1,0,1]
	v_cvt_pk_bf16_f32 v136, v60, v61
	v_cvt_pk_bf16_f32 v137, v62, v63
	v_cvt_pk_bf16_f32 v138, v56, v57
	v_cvt_pk_bf16_f32 v139, v58, v59
	global_store_dwordx4 v[176:177], v[136:139], off offset:256
	global_load_dwordx4 v[234:237], v[190:191], off offset:256
	global_load_dwordx4 v[246:249], v[202:203], off offset:256
	global_load_dwordx4 v[242:245], v[196:197], off offset:256
	global_load_dwordx4 v[238:241], v[192:193], off offset:256
	s_waitcnt vmcnt(3)
	v_lshlrev_b32_e32 v140, 16, v234
	v_and_b32_e32 v136, 0xffff0000, v234
	v_lshlrev_b32_e32 v141, 16, v235
	v_and_b32_e32 v142, 0xffff0000, v235
	v_lshlrev_b32_e32 v143, 16, v236
	v_and_b32_e32 v176, 0xffff0000, v236
	v_lshlrev_b32_e32 v177, 16, v237
	v_and_b32_e32 v186, 0xffff0000, v237
	v_sub_f32_e32 v137, v136, v195
	v_sub_f32_e32 v136, v140, v195
	v_sub_f32_e32 v139, v142, v195
	v_sub_f32_e32 v138, v141, v195
	v_sub_f32_e32 v141, v176, v195
	v_sub_f32_e32 v140, v143, v195
	v_sub_f32_e32 v143, v186, v195
	v_sub_f32_e32 v142, v177, v195
	v_pk_mul_f32 v[138:139], v[194:195], v[138:139] op_sel_hi:[0,1]
	v_pk_mul_f32 v[136:137], v[194:195], v[136:137] op_sel_hi:[0,1]
	v_pk_mul_f32 v[142:143], v[194:195], v[142:143] op_sel_hi:[0,1]
	v_pk_mul_f32 v[140:141], v[194:195], v[140:141] op_sel_hi:[0,1]
	v_pk_fma_f32 v[136:137], v[72:73], v[136:137], v[68:69]
	v_pk_fma_f32 v[138:139], v[74:75], v[138:139], v[70:71]
	v_pk_fma_f32 v[140:141], v[64:65], v[140:141], v[76:77]
	v_pk_fma_f32 v[142:143], v[66:67], v[142:143], v[78:79]
	v_pk_fma_f32 v[54:55], v[138:139], s[34:35], v[54:55] op_sel_hi:[1,0,1]
	v_pk_fma_f32 v[52:53], v[136:137], s[34:35], v[52:53] op_sel_hi:[1,0,1]
	v_pk_fma_f32 v[50:51], v[142:143], s[34:35], v[50:51] op_sel_hi:[1,0,1]
	v_pk_fma_f32 v[48:49], v[140:141], s[34:35], v[48:49] op_sel_hi:[1,0,1]
	v_cvt_pk_bf16_f32 v136, v52, v53
	v_cvt_pk_bf16_f32 v137, v54, v55
	v_cvt_pk_bf16_f32 v138, v48, v49
	v_cvt_pk_bf16_f32 v139, v50, v51
	global_store_dwordx4 v[190:191], v[136:139], off offset:256
	s_nop 0
	global_load_dwordx4 v[234:237], v[206:207], off offset:256
	s_waitcnt vmcnt(2)
	v_lshlrev_b32_e32 v140, 16, v238
	v_and_b32_e32 v136, 0xffff0000, v238
	v_lshlrev_b32_e32 v141, 16, v239
	v_and_b32_e32 v142, 0xffff0000, v239
	v_lshlrev_b32_e32 v143, 16, v240
	v_and_b32_e32 v176, 0xffff0000, v240
	v_lshlrev_b32_e32 v177, 16, v241
	v_and_b32_e32 v186, 0xffff0000, v241
	v_sub_f32_e32 v137, v136, v199
	v_sub_f32_e32 v136, v140, v199
	v_sub_f32_e32 v139, v142, v199
	v_sub_f32_e32 v138, v141, v199
	v_sub_f32_e32 v141, v176, v199
	v_sub_f32_e32 v140, v143, v199
	v_sub_f32_e32 v143, v186, v199
	v_sub_f32_e32 v142, v177, v199
	v_pk_mul_f32 v[138:139], v[198:199], v[138:139] op_sel_hi:[0,1]
	v_pk_mul_f32 v[136:137], v[198:199], v[136:137] op_sel_hi:[0,1]
	v_pk_mul_f32 v[142:143], v[198:199], v[142:143] op_sel_hi:[0,1]
	v_pk_mul_f32 v[140:141], v[198:199], v[140:141] op_sel_hi:[0,1]
	v_pk_fma_f32 v[136:137], v[72:73], v[136:137], v[68:69]
	v_pk_fma_f32 v[138:139], v[74:75], v[138:139], v[70:71]
	v_pk_fma_f32 v[140:141], v[64:65], v[140:141], v[76:77]
	v_pk_fma_f32 v[142:143], v[66:67], v[142:143], v[78:79]
	v_pk_fma_f32 v[46:47], v[138:139], s[34:35], v[46:47] op_sel_hi:[1,0,1]
	v_pk_fma_f32 v[44:45], v[136:137], s[34:35], v[44:45] op_sel_hi:[1,0,1]
	v_pk_fma_f32 v[42:43], v[142:143], s[34:35], v[42:43] op_sel_hi:[1,0,1]
	v_pk_fma_f32 v[40:41], v[140:141], s[34:35], v[40:41] op_sel_hi:[1,0,1]
	v_cvt_pk_bf16_f32 v136, v44, v45
	v_cvt_pk_bf16_f32 v137, v46, v47
	v_cvt_pk_bf16_f32 v138, v40, v41
	v_cvt_pk_bf16_f32 v139, v42, v43
	global_store_dwordx4 v[192:193], v[136:139], off offset:256
	s_nop 0
	global_load_dwordx4 v[238:241], v[212:213], off offset:256
	s_waitcnt vmcnt(5)
	v_lshlrev_b32_e32 v140, 16, v242
	v_and_b32_e32 v136, 0xffff0000, v242
	v_lshlrev_b32_e32 v141, 16, v243
	v_and_b32_e32 v142, 0xffff0000, v243
	v_lshlrev_b32_e32 v143, 16, v244
	v_and_b32_e32 v176, 0xffff0000, v244
	v_lshlrev_b32_e32 v177, 16, v245
	v_and_b32_e32 v186, 0xffff0000, v245
	v_sub_f32_e32 v137, v136, v205
	v_sub_f32_e32 v136, v140, v205
	v_sub_f32_e32 v139, v142, v205
	v_sub_f32_e32 v138, v141, v205
	v_sub_f32_e32 v141, v176, v205
	v_sub_f32_e32 v140, v143, v205
	v_sub_f32_e32 v143, v186, v205
	v_sub_f32_e32 v142, v177, v205
	v_pk_mul_f32 v[138:139], v[204:205], v[138:139] op_sel_hi:[0,1]
	v_pk_mul_f32 v[136:137], v[204:205], v[136:137] op_sel_hi:[0,1]
	v_pk_mul_f32 v[142:143], v[204:205], v[142:143] op_sel_hi:[0,1]
	v_pk_mul_f32 v[140:141], v[204:205], v[140:141] op_sel_hi:[0,1]
	v_pk_fma_f32 v[136:137], v[72:73], v[136:137], v[68:69]
	v_pk_fma_f32 v[138:139], v[74:75], v[138:139], v[70:71]
	v_pk_fma_f32 v[140:141], v[64:65], v[140:141], v[76:77]
	v_pk_fma_f32 v[142:143], v[66:67], v[142:143], v[78:79]
	v_pk_fma_f32 v[38:39], v[138:139], s[34:35], v[38:39] op_sel_hi:[1,0,1]
	v_pk_fma_f32 v[36:37], v[136:137], s[34:35], v[36:37] op_sel_hi:[1,0,1]
	v_pk_fma_f32 v[34:35], v[142:143], s[34:35], v[34:35] op_sel_hi:[1,0,1]
	v_pk_fma_f32 v[32:33], v[140:141], s[34:35], v[32:33] op_sel_hi:[1,0,1]
	v_cvt_pk_bf16_f32 v136, v36, v37
	v_cvt_pk_bf16_f32 v137, v38, v39
	v_cvt_pk_bf16_f32 v138, v32, v33
	v_cvt_pk_bf16_f32 v139, v34, v35
	global_store_dwordx4 v[196:197], v[136:139], off offset:256
	s_nop 0
	global_load_dwordx4 v[242:245], v[210:211], off offset:256
	s_waitcnt vmcnt(8)
	v_lshlrev_b32_e32 v140, 16, v246
	v_and_b32_e32 v136, 0xffff0000, v246
	v_lshlrev_b32_e32 v141, 16, v247
	v_and_b32_e32 v142, 0xffff0000, v247
	v_lshlrev_b32_e32 v143, 16, v248
	v_and_b32_e32 v176, 0xffff0000, v248
	v_lshlrev_b32_e32 v177, 16, v249
	v_and_b32_e32 v186, 0xffff0000, v249
	v_sub_f32_e32 v137, v136, v209
	v_sub_f32_e32 v136, v140, v209
	v_sub_f32_e32 v139, v142, v209
	v_sub_f32_e32 v138, v141, v209
	v_sub_f32_e32 v141, v176, v209
	v_sub_f32_e32 v140, v143, v209
	v_sub_f32_e32 v143, v186, v209
	v_sub_f32_e32 v142, v177, v209
	v_pk_mul_f32 v[138:139], v[208:209], v[138:139] op_sel_hi:[0,1]
	v_pk_mul_f32 v[136:137], v[208:209], v[136:137] op_sel_hi:[0,1]
	v_pk_mul_f32 v[142:143], v[208:209], v[142:143] op_sel_hi:[0,1]
	v_pk_mul_f32 v[140:141], v[208:209], v[140:141] op_sel_hi:[0,1]
	v_pk_fma_f32 v[136:137], v[72:73], v[136:137], v[68:69]
	v_pk_fma_f32 v[138:139], v[74:75], v[138:139], v[70:71]
	v_pk_fma_f32 v[140:141], v[64:65], v[140:141], v[76:77]
	v_pk_fma_f32 v[142:143], v[66:67], v[142:143], v[78:79]
	v_pk_fma_f32 v[30:31], v[138:139], s[34:35], v[30:31] op_sel_hi:[1,0,1]
	v_pk_fma_f32 v[28:29], v[136:137], s[34:35], v[28:29] op_sel_hi:[1,0,1]
	v_pk_fma_f32 v[26:27], v[142:143], s[34:35], v[26:27] op_sel_hi:[1,0,1]
	v_pk_fma_f32 v[24:25], v[140:141], s[34:35], v[24:25] op_sel_hi:[1,0,1]
	v_cvt_pk_bf16_f32 v136, v28, v29
	v_cvt_pk_bf16_f32 v137, v30, v31
	v_cvt_pk_bf16_f32 v138, v24, v25
	v_cvt_pk_bf16_f32 v139, v26, v27
	global_store_dwordx4 v[202:203], v[136:139], off offset:256
	s_nop 0
	s_waitcnt vmcnt(5)
	v_lshlrev_b32_e32 v140, 16, v234
	v_and_b32_e32 v136, 0xffff0000, v234
	v_lshlrev_b32_e32 v141, 16, v235
	v_and_b32_e32 v142, 0xffff0000, v235
	v_lshlrev_b32_e32 v143, 16, v236
	v_and_b32_e32 v176, 0xffff0000, v236
	v_lshlrev_b32_e32 v177, 16, v237
	v_and_b32_e32 v186, 0xffff0000, v237
	v_sub_f32_e32 v137, v136, v215
	v_sub_f32_e32 v136, v140, v215
	v_sub_f32_e32 v139, v142, v215
	v_sub_f32_e32 v138, v141, v215
	v_sub_f32_e32 v141, v176, v215
	v_sub_f32_e32 v140, v143, v215
	v_sub_f32_e32 v143, v186, v215
	v_sub_f32_e32 v142, v177, v215
	v_pk_mul_f32 v[138:139], v[214:215], v[138:139] op_sel_hi:[0,1]
	v_pk_mul_f32 v[136:137], v[214:215], v[136:137] op_sel_hi:[0,1]
	v_pk_mul_f32 v[142:143], v[214:215], v[142:143] op_sel_hi:[0,1]
	v_pk_mul_f32 v[140:141], v[214:215], v[140:141] op_sel_hi:[0,1]
	v_pk_fma_f32 v[136:137], v[72:73], v[136:137], v[68:69]
	v_pk_fma_f32 v[138:139], v[74:75], v[138:139], v[70:71]
	v_pk_fma_f32 v[140:141], v[64:65], v[140:141], v[76:77]
	v_pk_fma_f32 v[142:143], v[66:67], v[142:143], v[78:79]
	v_pk_fma_f32 v[22:23], v[138:139], s[34:35], v[22:23] op_sel_hi:[1,0,1]
	v_pk_fma_f32 v[20:21], v[136:137], s[34:35], v[20:21] op_sel_hi:[1,0,1]
	v_pk_fma_f32 v[18:19], v[142:143], s[34:35], v[18:19] op_sel_hi:[1,0,1]
	v_pk_fma_f32 v[16:17], v[140:141], s[34:35], v[16:17] op_sel_hi:[1,0,1]
	v_cvt_pk_bf16_f32 v136, v20, v21
	v_cvt_pk_bf16_f32 v137, v22, v23
	v_cvt_pk_bf16_f32 v138, v16, v17
	v_cvt_pk_bf16_f32 v139, v18, v19
	global_store_dwordx4 v[206:207], v[136:139], off offset:256
	s_nop 0
	s_waitcnt vmcnt(4)
	v_lshlrev_b32_e32 v140, 16, v238
	v_and_b32_e32 v136, 0xffff0000, v238
	v_lshlrev_b32_e32 v141, 16, v239
	v_and_b32_e32 v142, 0xffff0000, v239
	v_lshlrev_b32_e32 v143, 16, v240
	v_and_b32_e32 v176, 0xffff0000, v240
	v_lshlrev_b32_e32 v177, 16, v241
	v_and_b32_e32 v186, 0xffff0000, v241
	v_sub_f32_e32 v137, v136, v217
	v_sub_f32_e32 v136, v140, v217
	v_sub_f32_e32 v139, v142, v217
	v_sub_f32_e32 v138, v141, v217
	v_sub_f32_e32 v141, v176, v217
	v_sub_f32_e32 v140, v143, v217
	v_sub_f32_e32 v143, v186, v217
	v_sub_f32_e32 v142, v177, v217
	v_pk_mul_f32 v[138:139], v[216:217], v[138:139] op_sel_hi:[0,1]
	v_pk_mul_f32 v[136:137], v[216:217], v[136:137] op_sel_hi:[0,1]
	v_pk_mul_f32 v[142:143], v[216:217], v[142:143] op_sel_hi:[0,1]
	v_pk_mul_f32 v[140:141], v[216:217], v[140:141] op_sel_hi:[0,1]
	v_pk_fma_f32 v[136:137], v[72:73], v[136:137], v[68:69]
	v_pk_fma_f32 v[138:139], v[74:75], v[138:139], v[70:71]
	v_pk_fma_f32 v[140:141], v[64:65], v[140:141], v[76:77]
	v_pk_fma_f32 v[142:143], v[66:67], v[142:143], v[78:79]
	v_pk_fma_f32 v[14:15], v[138:139], s[34:35], v[14:15] op_sel_hi:[1,0,1]
	v_pk_fma_f32 v[12:13], v[136:137], s[34:35], v[12:13] op_sel_hi:[1,0,1]
	v_pk_fma_f32 v[10:11], v[142:143], s[34:35], v[10:11] op_sel_hi:[1,0,1]
	v_pk_fma_f32 v[8:9], v[140:141], s[34:35], v[8:9] op_sel_hi:[1,0,1]
	v_cvt_pk_bf16_f32 v136, v12, v13
	v_cvt_pk_bf16_f32 v137, v14, v15
	v_cvt_pk_bf16_f32 v138, v8, v9
	v_cvt_pk_bf16_f32 v139, v10, v11
	global_store_dwordx4 v[212:213], v[136:139], off offset:256
	s_nop 0
	v_add_f32_e32 v140, v124, v125
	v_add_f32_e32 v141, v126, v127
	v_add_f32_e32 v142, v120, v121
	v_add_f32_e32 v143, v122, v123
	v_mul_f32_e32 v125, v125, v125
	v_mul_f32_e32 v127, v127, v127
	v_mul_f32_e32 v121, v121, v121
	v_mul_f32_e32 v123, v123, v123
	v_fmac_f32_e32 v125, v124, v124
	v_fmac_f32_e32 v127, v126, v126
	v_fmac_f32_e32 v121, v120, v120
	v_fmac_f32_e32 v123, v122, v122
	v_add_f32_e32 v122, v125, v127
	v_add_f32_e32 v121, v121, v123
	v_add_f32_e32 v121, v122, v121
	v_add_f32_e32 v122, v60, v61
	v_add_f32_e32 v123, v62, v63
	v_add_f32_e32 v124, v56, v57
	v_add_f32_e32 v125, v58, v59
	v_mul_f32_e32 v61, v61, v61
	v_mul_f32_e32 v63, v63, v63
	v_mul_f32_e32 v57, v57, v57
	v_mul_f32_e32 v59, v59, v59
	v_add_f32_e32 v140, v140, v141
	v_add_f32_e32 v141, v142, v143
	v_fmac_f32_e32 v61, v60, v60
	v_fmac_f32_e32 v63, v62, v62
	v_fmac_f32_e32 v57, v56, v56
	v_fmac_f32_e32 v59, v58, v58
	v_add_f32_e32 v120, v140, v141
	v_add_f32_e32 v122, v122, v123
	v_add_f32_e32 v123, v124, v125
	v_add_f32_e32 v58, v61, v63
	v_add_f32_e32 v57, v57, v59
	v_add_f32_e32 v120, 0, v120
	v_add_f32_e32 v56, v122, v123
	v_add_f32_e32 v57, v58, v57
	v_add_f32_e32 v56, v120, v56
	v_add_f32_e32 v59, v121, v57
	ds_bpermute_b32 v58, v222, v56
	ds_bpermute_b32 v60, v222, v59
	s_waitcnt lgkmcnt(0)
	v_add_f32_e32 v56, v56, v58
	v_add_f32_e32 v58, v59, v60
	ds_bpermute_b32 v57, v221, v56
	s_waitcnt vmcnt(3)
	v_lshlrev_b32_e32 v59, 16, v242
	v_and_b32_e32 v60, 0xffff0000, v242
	v_lshlrev_b32_e32 v62, 16, v243
	v_and_b32_e32 v63, 0xffff0000, v243
	v_lshlrev_b32_e32 v120, 16, v244
	v_and_b32_e32 v121, 0xffff0000, v244
	v_lshlrev_b32_e32 v122, 16, v245
	v_and_b32_e32 v123, 0xffff0000, v245
	v_sub_f32_e32 v61, v60, v201
	v_sub_f32_e32 v60, v59, v201
	v_sub_f32_e32 v63, v63, v201
	v_sub_f32_e32 v62, v62, v201
	v_sub_f32_e32 v121, v121, v201
	v_sub_f32_e32 v120, v120, v201
	v_sub_f32_e32 v123, v123, v201
	v_sub_f32_e32 v122, v122, v201
	v_pk_mul_f32 v[62:63], v[200:201], v[62:63] op_sel_hi:[0,1]
	v_pk_mul_f32 v[60:61], v[200:201], v[60:61] op_sel_hi:[0,1]
	v_pk_mul_f32 v[122:123], v[200:201], v[122:123] op_sel_hi:[0,1]
	v_pk_mul_f32 v[120:121], v[200:201], v[120:121] op_sel_hi:[0,1]
	v_pk_fma_f32 v[60:61], v[72:73], v[60:61], v[68:69]
	v_pk_fma_f32 v[62:63], v[74:75], v[62:63], v[70:71]
	v_pk_fma_f32 v[64:65], v[64:65], v[120:121], v[76:77]
	v_pk_fma_f32 v[66:67], v[66:67], v[122:123], v[78:79]
	v_pk_fma_f32 v[6:7], v[62:63], s[34:35], v[6:7] op_sel_hi:[1,0,1]
	v_pk_fma_f32 v[4:5], v[60:61], s[34:35], v[4:5] op_sel_hi:[1,0,1]
	v_pk_fma_f32 v[2:3], v[66:67], s[34:35], v[2:3] op_sel_hi:[1,0,1]
	v_pk_fma_f32 v[0:1], v[64:65], s[34:35], v[0:1] op_sel_hi:[1,0,1]
	v_cvt_pk_bf16_f32 v60, v4, v5
	v_cvt_pk_bf16_f32 v61, v6, v7
	v_cvt_pk_bf16_f32 v62, v0, v1
	v_cvt_pk_bf16_f32 v63, v2, v3
	ds_bpermute_b32 v59, v221, v58
	global_store_dwordx4 v[210:211], v[60:63], off offset:256
	s_and_saveexec_b64 s[0:1], s[4:5]
	s_cbranch_execz .LBB0_1477
	s_waitcnt lgkmcnt(0)
	v_add_f32_e32 v58, v58, v59
	v_add_f32_e32 v59, v56, v57
	v_lshl_add_u64 v[56:57], s[22:23], 0, v[164:165]
	global_atomic_add_f32 v[56:57], v59, off
	global_atomic_add_f32 v[56:57], v58, off offset:4
